# same as the interleaved-XCD version but without the 64-cycle stagger sleep in the scan waves
# baseline (speedup 1.0000x reference)
; #define LAS __attribute__((address_space(3)))
; __device__ __forceinline__ void phase_scan(CParams& P, LAS unsigned char* lds) {
;     ...
;             for (int c = 0; c < NCH; ++c) {
;                 __syncthreads();
;                 if (c + 1 < NCH) { SC_WRITE(c + 1); if (c + 2 < NCH) SC_GLOAD(c + 2); }
;             }
;             __syncthreads();
;     ...
;         } else {
;             const int rl = lane >> 3, oct = lane & 7, rloc = wid * 8 + rl;
;             __builtin_amdgcn_s_setprio(3);
;             f32x4 s0 = {0.f, 0.f, 0.f, 0.f}, s1 = {0.f, 0.f, 0.f, 0.f};
;             float* op = OUT + ((size_t)s * SEQ + (dir ? SEQ - 1 : 0)) * 512 + h * 64 + rowhalf * 32 + rloc; const long ostep = dir ? -512 : 512;
;     ...
;             f32x4 Ar0, Ar1, Aw0, Aw1, Ak0, Ak1, Aq0, Aq1, Ab0, Ab1, Br0, Br1, Bw0, Bw1, Bk0, Bk1, Bq0, Bq1, Bb0, Bb1; float Avv, Bvv;
; #pragma unroll 1
;             for (int c = 0; c < NCH; ++c) {
;                 __syncthreads();
;                 const LAS float* base = lf + (c & 1) * BUFF + 8 * oct;
;                 SC_LOAD(A, base);
; #pragma unroll 2
;                 for (int j = 0; j < CH; j += 2) { const LAS float* sp = base + j * STEPF;
;                     SC_LOAD(B, sp + STEPF); SC_STEP(A);
;                     SC_LOAD(A, sp + 2 * STEPF);
;                     SC_STEP(B); }
.Lr3_cwdone2:
	s_cmp_ge_u32 s12, 0x7e
	s_cbranch_scc1 .Lr3_noload
	global_load_dwordx4 v[158:161], v[152:153], off
	global_load_dwordx4 v[162:165], v[154:155], off
	global_load_dwordx4 v[166:169], v[156:157], off
	v_lshl_add_u64 v[152:153], v[152:153], 0, s[48:49]
	v_lshl_add_u64 v[154:155], v[154:155], 0, s[48:49]
	v_lshl_add_u64 v[156:157], v[156:157], 0, s[36:37]
.Lr3_noload:
	s_waitcnt lgkmcnt(0)
	v_pk_mul_f32 v[78:79], v[2:3], v[10:11] op_sel_hi:[1,0]
	v_pk_fma_f32 v[78:79], v[4:5], v[10:11], v[78:79] op_sel:[0,1,0] op_sel_hi:[1,1,1]
	v_pk_fma_f32 v[78:79], v[6:7], v[12:13], v[78:79] op_sel_hi:[1,0,1]
	v_pk_fma_f32 v[78:79], v[8:9], v[12:13], v[78:79] op_sel:[0,1,0] op_sel_hi:[1,1,1]
	v_pk_mul_f32 v[82:83], v[70:71], v[18:19] op_sel_hi:[1,0]
	v_pk_mul_f32 v[84:85], v[70:71], v[18:19] op_sel:[0,1] op_sel_hi:[1,1]
	v_add_f32_dpp v78, v78, v78 quad_perm:[1,0,3,2] row_mask:0xf bank_mask:0xf bound_ctrl:1
	v_add_f32_dpp v79, v79, v79 quad_perm:[1,0,3,2] row_mask:0xf bank_mask:0xf bound_ctrl:1
	v_pk_mul_f32 v[86:87], v[70:71], v[20:21] op_sel_hi:[1,0]
	ds_read_b128 v[132:135], v100 offset:2560
	v_add_f32_dpp v78, v78, v78 quad_perm:[2,3,0,1] row_mask:0xf bank_mask:0xf bound_ctrl:1
	v_add_f32_dpp v79, v79, v79 quad_perm:[2,3,0,1] row_mask:0xf bank_mask:0xf bound_ctrl:1
	v_pk_mul_f32 v[88:89], v[70:71], v[20:21] op_sel:[0,1] op_sel_hi:[1,1]
	ds_read_b128 v[140:143], v100 offset:3072
	v_add_f32_dpp v78, v78, v78 row_half_mirror row_mask:0xf bank_mask:0xf bound_ctrl:1
	v_add_f32_dpp v79, v79, v79 row_half_mirror row_mask:0xf bank_mask:0xf bound_ctrl:1
	v_pk_fma_f32 v[82:83], v[2:3], v[14:15], v[82:83] op_sel_hi:[1,0,1]
	ds_read_b128 v[136:139], v100 offset:2816
	v_add_f32_dpp v78, v78, v78 row_mirror row_mask:0xf bank_mask:0xf bound_ctrl:1
	v_add_f32_dpp v79, v79, v79 row_mirror row_mask:0xf bank_mask:0xf bound_ctrl:1
	v_pk_fma_f32 v[84:85], v[4:5], v[14:15], v[84:85] op_sel:[0,1,0] op_sel_hi:[1,1,1]
	ds_read_b128 v[144:147], v100 offset:3328
	v_pk_fma_f32 v[86:87], v[6:7], v[16:17], v[86:87] op_sel_hi:[1,0,1]
	ds_read_b128 v[148:151], v100 offset:3584
	v_pk_fma_f32 v[88:89], v[8:9], v[16:17], v[88:89] op_sel:[0,1,0] op_sel_hi:[1,1,1]
	ds_read_b128 v[74:77], v101 offset:16
	v_pk_fma_f32 v[2:3], v[78:79], v[22:23], v[82:83] op_sel_hi:[1,0,1]
	v_pk_fma_f32 v[4:5], v[78:79], v[22:23], v[84:85] op_sel:[0,1,0] op_sel_hi:[1,1,1]
	v_pk_fma_f32 v[6:7], v[78:79], v[24:25], v[86:87] op_sel_hi:[1,0,1]
	v_pk_fma_f32 v[8:9], v[78:79], v[24:25], v[88:89] op_sel:[0,1,0] op_sel_hi:[1,1,1]
	s_waitcnt lgkmcnt(6)
	v_pk_mul_f32 v[78:79], v[2:3], v[30:31] op_sel_hi:[1,0]
	v_pk_mul_f32 v[90:91], v[2:3], v[26:27] op_sel_hi:[1,0]
	v_pk_fma_f32 v[78:79], v[4:5], v[30:31], v[78:79] op_sel:[0,1,0] op_sel_hi:[1,1,1]
	v_pk_fma_f32 v[90:91], v[4:5], v[26:27], v[90:91] op_sel:[0,1,0] op_sel_hi:[1,1,1]
	v_pk_fma_f32 v[78:79], v[6:7], v[32:33], v[78:79] op_sel_hi:[1,0,1]
	v_pk_fma_f32 v[90:91], v[6:7], v[28:29], v[90:91] op_sel_hi:[1,0,1]
	v_pk_fma_f32 v[78:79], v[8:9], v[32:33], v[78:79] op_sel:[0,1,0] op_sel_hi:[1,1,1]
	v_pk_mul_f32 v[82:83], v[72:73], v[38:39] op_sel_hi:[1,0]
	v_pk_fma_f32 v[90:91], v[8:9], v[28:29], v[90:91] op_sel:[0,1,0] op_sel_hi:[1,1,1]
	v_pk_mul_f32 v[84:85], v[72:73], v[38:39] op_sel:[0,1] op_sel_hi:[1,1]
	v_add_f32_dpp v78, v78, v78 quad_perm:[1,0,3,2] row_mask:0xf bank_mask:0xf bound_ctrl:1
	v_add_f32_dpp v79, v79, v79 quad_perm:[1,0,3,2] row_mask:0xf bank_mask:0xf bound_ctrl:1
	v_pk_mul_f32 v[86:87], v[72:73], v[40:41] op_sel_hi:[1,0]
	ds_read_b128 v[10:13], v100 offset:3840
	v_add_f32_dpp v78, v78, v78 quad_perm:[2,3,0,1] row_mask:0xf bank_mask:0xf bound_ctrl:1
	v_add_f32_dpp v79, v79, v79 quad_perm:[2,3,0,1] row_mask:0xf bank_mask:0xf bound_ctrl:1
	v_pk_mul_f32 v[88:89], v[72:73], v[40:41] op_sel:[0,1] op_sel_hi:[1,1]
	ds_read_b128 v[18:21], v100 offset:4352
	v_add_f32_dpp v78, v78, v78 row_half_mirror row_mask:0xf bank_mask:0xf bound_ctrl:1
	v_add_f32_dpp v79, v79, v79 row_half_mirror row_mask:0xf bank_mask:0xf bound_ctrl:1
	v_pk_fma_f32 v[82:83], v[2:3], v[34:35], v[82:83] op_sel_hi:[1,0,1]
	ds_read_b128 v[14:17], v100 offset:4096
	v_add_f32_dpp v78, v78, v78 row_mirror row_mask:0xf bank_mask:0xf bound_ctrl:1
	v_add_f32_dpp v79, v79, v79 row_mirror row_mask:0xf bank_mask:0xf bound_ctrl:1
	v_pk_fma_f32 v[84:85], v[4:5], v[34:35], v[84:85] op_sel:[0,1,0] op_sel_hi:[1,1,1]
	ds_read_b128 v[22:25], v100 offset:4608
	v_pk_fma_f32 v[86:87], v[6:7], v[36:37], v[86:87] op_sel_hi:[1,0,1]
	ds_read_b128 v[26:29], v100 offset:4864
	v_pk_fma_f32 v[88:89], v[8:9], v[36:37], v[88:89] op_sel:[0,1,0] op_sel_hi:[1,1,1]
	v_pk_fma_f32 v[2:3], v[78:79], v[42:43], v[82:83] op_sel_hi:[1,0,1]
	v_pk_fma_f32 v[4:5], v[78:79], v[42:43], v[84:85] op_sel:[0,1,0] op_sel_hi:[1,1,1]
	v_pk_fma_f32 v[6:7], v[78:79], v[44:45], v[86:87] op_sel_hi:[1,0,1]
	v_pk_fma_f32 v[8:9], v[78:79], v[44:45], v[88:89] op_sel:[0,1,0] op_sel_hi:[1,1,1]
	s_waitcnt lgkmcnt(5)
; #define LAS __attribute__((address_space(3)))
; __device__ __forceinline__ void phase_scan(CParams& P, LAS unsigned char* lds) {
;     ...
; #pragma unroll 2
;                 for (int j = 0; j < CH; j += 2) { const LAS float* sp = base + j * STEPF;
;                     SC_LOAD(B, sp + STEPF); SC_STEP(A);
;                     SC_LOAD(A, sp + 2 * STEPF);
;                     SC_STEP(B); }
	v_pk_mul_f32 v[78:79], v[2:3], v[132:133] op_sel_hi:[1,0]
	v_pk_mul_f32 v[92:93], v[2:3], v[46:47] op_sel_hi:[1,0]
	v_pk_fma_f32 v[78:79], v[4:5], v[132:133], v[78:79] op_sel:[0,1,0] op_sel_hi:[1,1,1]
	v_pk_fma_f32 v[92:93], v[4:5], v[46:47], v[92:93] op_sel:[0,1,0] op_sel_hi:[1,1,1]
	v_pk_fma_f32 v[78:79], v[6:7], v[134:135], v[78:79] op_sel_hi:[1,0,1]
	v_pk_fma_f32 v[92:93], v[6:7], v[48:49], v[92:93] op_sel_hi:[1,0,1]
	v_pk_fma_f32 v[78:79], v[8:9], v[134:135], v[78:79] op_sel:[0,1,0] op_sel_hi:[1,1,1]
	v_pk_mul_f32 v[82:83], v[74:75], v[140:141] op_sel_hi:[1,0]
	v_pk_fma_f32 v[92:93], v[8:9], v[48:49], v[92:93] op_sel:[0,1,0] op_sel_hi:[1,1,1]
	v_pk_mul_f32 v[84:85], v[74:75], v[140:141] op_sel:[0,1] op_sel_hi:[1,1]
	v_add_f32_dpp v78, v78, v78 quad_perm:[1,0,3,2] row_mask:0xf bank_mask:0xf bound_ctrl:1
	v_add_f32_dpp v79, v79, v79 quad_perm:[1,0,3,2] row_mask:0xf bank_mask:0xf bound_ctrl:1
	v_pk_mul_f32 v[86:87], v[74:75], v[142:143] op_sel_hi:[1,0]
	ds_read_b128 v[30:33], v100 offset:5120
	v_add_f32_dpp v78, v78, v78 quad_perm:[2,3,0,1] row_mask:0xf bank_mask:0xf bound_ctrl:1
	v_add_f32_dpp v79, v79, v79 quad_perm:[2,3,0,1] row_mask:0xf bank_mask:0xf bound_ctrl:1
	v_pk_mul_f32 v[88:89], v[74:75], v[142:143] op_sel:[0,1] op_sel_hi:[1,1]
	ds_read_b128 v[38:41], v100 offset:5632
	v_add_f32_dpp v78, v78, v78 row_half_mirror row_mask:0xf bank_mask:0xf bound_ctrl:1
	v_add_f32_dpp v79, v79, v79 row_half_mirror row_mask:0xf bank_mask:0xf bound_ctrl:1
	v_pk_fma_f32 v[82:83], v[2:3], v[136:137], v[82:83] op_sel_hi:[1,0,1]
	ds_read_b128 v[34:37], v100 offset:5376
	v_add_f32_dpp v78, v78, v78 row_mirror row_mask:0xf bank_mask:0xf bound_ctrl:1
	v_add_f32_dpp v79, v79, v79 row_mirror row_mask:0xf bank_mask:0xf bound_ctrl:1
	v_pk_fma_f32 v[84:85], v[4:5], v[136:137], v[84:85] op_sel:[0,1,0] op_sel_hi:[1,1,1]
	ds_read_b128 v[42:45], v100 offset:5888
	v_pk_fma_f32 v[86:87], v[6:7], v[138:139], v[86:87] op_sel_hi:[1,0,1]
	ds_read_b128 v[46:49], v100 offset:6144
	v_pk_fma_f32 v[88:89], v[8:9], v[138:139], v[88:89] op_sel:[0,1,0] op_sel_hi:[1,1,1]
	ds_read_b128 v[70:73], v101 offset:32
	v_pk_fma_f32 v[2:3], v[78:79], v[144:145], v[82:83] op_sel_hi:[1,0,1]
	v_pk_fma_f32 v[4:5], v[78:79], v[144:145], v[84:85] op_sel:[0,1,0] op_sel_hi:[1,1,1]
	v_pk_fma_f32 v[6:7], v[78:79], v[146:147], v[86:87] op_sel_hi:[1,0,1]
	v_pk_fma_f32 v[8:9], v[78:79], v[146:147], v[88:89] op_sel:[0,1,0] op_sel_hi:[1,1,1]
	s_waitcnt lgkmcnt(6)
	v_pk_mul_f32 v[78:79], v[2:3], v[10:11] op_sel_hi:[1,0]
	v_pk_mul_f32 v[94:95], v[2:3], v[148:149] op_sel_hi:[1,0]
	v_pk_fma_f32 v[78:79], v[4:5], v[10:11], v[78:79] op_sel:[0,1,0] op_sel_hi:[1,1,1]
	v_pk_fma_f32 v[94:95], v[4:5], v[148:149], v[94:95] op_sel:[0,1,0] op_sel_hi:[1,1,1]
	v_pk_fma_f32 v[78:79], v[6:7], v[12:13], v[78:79] op_sel_hi:[1,0,1]
	v_pk_fma_f32 v[94:95], v[6:7], v[150:151], v[94:95] op_sel_hi:[1,0,1]
	v_pk_fma_f32 v[78:79], v[8:9], v[12:13], v[78:79] op_sel:[0,1,0] op_sel_hi:[1,1,1]
	v_pk_mul_f32 v[82:83], v[76:77], v[18:19] op_sel_hi:[1,0]
	v_pk_fma_f32 v[94:95], v[8:9], v[150:151], v[94:95] op_sel:[0,1,0] op_sel_hi:[1,1,1]
	v_pk_mul_f32 v[84:85], v[76:77], v[18:19] op_sel:[0,1] op_sel_hi:[1,1]
	v_add_f32_dpp v78, v78, v78 quad_perm:[1,0,3,2] row_mask:0xf bank_mask:0xf bound_ctrl:1
	v_add_f32_dpp v79, v79, v79 quad_perm:[1,0,3,2] row_mask:0xf bank_mask:0xf bound_ctrl:1
	v_pk_mul_f32 v[86:87], v[76:77], v[20:21] op_sel_hi:[1,0]
	ds_read_b128 v[132:135], v100 offset:6400
	v_add_f32_dpp v78, v78, v78 quad_perm:[2,3,0,1] row_mask:0xf bank_mask:0xf bound_ctrl:1
	v_add_f32_dpp v79, v79, v79 quad_perm:[2,3,0,1] row_mask:0xf bank_mask:0xf bound_ctrl:1
	v_pk_mul_f32 v[88:89], v[76:77], v[20:21] op_sel:[0,1] op_sel_hi:[1,1]
	ds_read_b128 v[140:143], v100 offset:6912
	v_add_f32_dpp v78, v78, v78 row_half_mirror row_mask:0xf bank_mask:0xf bound_ctrl:1
	v_add_f32_dpp v79, v79, v79 row_half_mirror row_mask:0xf bank_mask:0xf bound_ctrl:1
	v_pk_fma_f32 v[82:83], v[2:3], v[14:15], v[82:83] op_sel_hi:[1,0,1]
	ds_read_b128 v[136:139], v100 offset:6656
	v_add_f32_dpp v78, v78, v78 row_mirror row_mask:0xf bank_mask:0xf bound_ctrl:1
	v_add_f32_dpp v79, v79, v79 row_mirror row_mask:0xf bank_mask:0xf bound_ctrl:1
	v_pk_fma_f32 v[84:85], v[4:5], v[14:15], v[84:85] op_sel:[0,1,0] op_sel_hi:[1,1,1]
	ds_read_b128 v[144:147], v100 offset:7168
	v_pk_fma_f32 v[86:87], v[6:7], v[16:17], v[86:87] op_sel_hi:[1,0,1]
	ds_read_b128 v[148:151], v100 offset:7424
	v_pk_fma_f32 v[88:89], v[8:9], v[16:17], v[88:89] op_sel:[0,1,0] op_sel_hi:[1,1,1]
	v_pk_fma_f32 v[2:3], v[78:79], v[22:23], v[82:83] op_sel_hi:[1,0,1]
	v_pk_fma_f32 v[4:5], v[78:79], v[22:23], v[84:85] op_sel:[0,1,0] op_sel_hi:[1,1,1]
	v_pk_fma_f32 v[6:7], v[78:79], v[24:25], v[86:87] op_sel_hi:[1,0,1]
	v_pk_fma_f32 v[8:9], v[78:79], v[24:25], v[88:89] op_sel:[0,1,0] op_sel_hi:[1,1,1]
	s_waitcnt lgkmcnt(5)
; #define LAS __attribute__((address_space(3)))
; __device__ __forceinline__ void phase_scan(CParams& P, LAS unsigned char* lds) {
;     ...
; #pragma unroll 2
;                 for (int j = 0; j < CH; j += 2) { const LAS float* sp = base + j * STEPF;
;                     SC_LOAD(B, sp + STEPF); SC_STEP(A);
;                     SC_LOAD(A, sp + 2 * STEPF);
;                     SC_STEP(B); }
	v_pk_mul_f32 v[78:79], v[2:3], v[30:31] op_sel_hi:[1,0]
	v_pk_mul_f32 v[96:97], v[2:3], v[26:27] op_sel_hi:[1,0]
	v_pk_fma_f32 v[78:79], v[4:5], v[30:31], v[78:79] op_sel:[0,1,0] op_sel_hi:[1,1,1]
	v_pk_fma_f32 v[96:97], v[4:5], v[26:27], v[96:97] op_sel:[0,1,0] op_sel_hi:[1,1,1]
	v_pk_fma_f32 v[78:79], v[6:7], v[32:33], v[78:79] op_sel_hi:[1,0,1]
	v_pk_fma_f32 v[96:97], v[6:7], v[28:29], v[96:97] op_sel_hi:[1,0,1]
	v_pk_fma_f32 v[78:79], v[8:9], v[32:33], v[78:79] op_sel:[0,1,0] op_sel_hi:[1,1,1]
	v_pk_mul_f32 v[82:83], v[70:71], v[38:39] op_sel_hi:[1,0]
	v_pk_fma_f32 v[96:97], v[8:9], v[28:29], v[96:97] op_sel:[0,1,0] op_sel_hi:[1,1,1]
	v_pk_mul_f32 v[84:85], v[70:71], v[38:39] op_sel:[0,1] op_sel_hi:[1,1]
	v_add_f32_dpp v78, v78, v78 quad_perm:[1,0,3,2] row_mask:0xf bank_mask:0xf bound_ctrl:1
	v_add_f32_dpp v79, v79, v79 quad_perm:[1,0,3,2] row_mask:0xf bank_mask:0xf bound_ctrl:1
	v_pk_mul_f32 v[86:87], v[70:71], v[40:41] op_sel_hi:[1,0]
	ds_read_b128 v[10:13], v100 offset:7680
	v_add_f32_dpp v78, v78, v78 quad_perm:[2,3,0,1] row_mask:0xf bank_mask:0xf bound_ctrl:1
	v_add_f32_dpp v79, v79, v79 quad_perm:[2,3,0,1] row_mask:0xf bank_mask:0xf bound_ctrl:1
	v_pk_mul_f32 v[88:89], v[70:71], v[40:41] op_sel:[0,1] op_sel_hi:[1,1]
	ds_read_b128 v[18:21], v100 offset:8192
	v_add_f32_dpp v78, v78, v78 row_half_mirror row_mask:0xf bank_mask:0xf bound_ctrl:1
	v_add_f32_dpp v79, v79, v79 row_half_mirror row_mask:0xf bank_mask:0xf bound_ctrl:1
	v_pk_fma_f32 v[82:83], v[2:3], v[34:35], v[82:83] op_sel_hi:[1,0,1]
	ds_read_b128 v[14:17], v100 offset:7936
	v_add_f32_dpp v78, v78, v78 row_mirror row_mask:0xf bank_mask:0xf bound_ctrl:1
	v_add_f32_dpp v79, v79, v79 row_mirror row_mask:0xf bank_mask:0xf bound_ctrl:1
	v_pk_fma_f32 v[84:85], v[4:5], v[34:35], v[84:85] op_sel:[0,1,0] op_sel_hi:[1,1,1]
	ds_read_b128 v[22:25], v100 offset:8448
	v_pk_fma_f32 v[86:87], v[6:7], v[36:37], v[86:87] op_sel_hi:[1,0,1]
	ds_read_b128 v[26:29], v100 offset:8704
	v_pk_fma_f32 v[88:89], v[8:9], v[36:37], v[88:89] op_sel:[0,1,0] op_sel_hi:[1,1,1]
	ds_read_b128 v[74:77], v101 offset:48
	v_cndmask_b32_e64 v104, v90, v92, s[50:51]
	v_cndmask_b32_e64 v106, v92, v90, s[50:51]
	v_cndmask_b32_e64 v108, v94, v96, s[50:51]
	v_pk_fma_f32 v[2:3], v[78:79], v[42:43], v[82:83] op_sel_hi:[1,0,1]
	v_pk_fma_f32 v[4:5], v[78:79], v[42:43], v[84:85] op_sel:[0,1,0] op_sel_hi:[1,1,1]
	v_pk_fma_f32 v[6:7], v[78:79], v[44:45], v[86:87] op_sel_hi:[1,0,1]
	v_pk_fma_f32 v[8:9], v[78:79], v[44:45], v[88:89] op_sel:[0,1,0] op_sel_hi:[1,1,1]
	v_cndmask_b32_e64 v110, v96, v94, s[50:51]
	v_cndmask_b32_e64 v105, v91, v93, s[50:51]
	v_cndmask_b32_e64 v107, v93, v91, s[50:51]
	s_waitcnt lgkmcnt(6)
	v_pk_mul_f32 v[78:79], v[2:3], v[132:133] op_sel_hi:[1,0]
	v_pk_mul_f32 v[90:91], v[2:3], v[46:47] op_sel_hi:[1,0]
	v_pk_fma_f32 v[78:79], v[4:5], v[132:133], v[78:79] op_sel:[0,1,0] op_sel_hi:[1,1,1]
	v_pk_fma_f32 v[90:91], v[4:5], v[46:47], v[90:91] op_sel:[0,1,0] op_sel_hi:[1,1,1]
	v_pk_fma_f32 v[78:79], v[6:7], v[134:135], v[78:79] op_sel_hi:[1,0,1]
	v_pk_fma_f32 v[90:91], v[6:7], v[48:49], v[90:91] op_sel_hi:[1,0,1]
	v_pk_fma_f32 v[78:79], v[8:9], v[134:135], v[78:79] op_sel:[0,1,0] op_sel_hi:[1,1,1]
	v_pk_mul_f32 v[82:83], v[72:73], v[140:141] op_sel_hi:[1,0]
	v_pk_fma_f32 v[90:91], v[8:9], v[48:49], v[90:91] op_sel:[0,1,0] op_sel_hi:[1,1,1]
	v_pk_mul_f32 v[84:85], v[72:73], v[140:141] op_sel:[0,1] op_sel_hi:[1,1]
	v_add_f32_dpp v78, v78, v78 quad_perm:[1,0,3,2] row_mask:0xf bank_mask:0xf bound_ctrl:1
	v_add_f32_dpp v79, v79, v79 quad_perm:[1,0,3,2] row_mask:0xf bank_mask:0xf bound_ctrl:1
	v_pk_mul_f32 v[86:87], v[72:73], v[142:143] op_sel_hi:[1,0]
	ds_read_b128 v[30:33], v100 offset:8960
	v_add_f32_dpp v78, v78, v78 quad_perm:[2,3,0,1] row_mask:0xf bank_mask:0xf bound_ctrl:1
	v_add_f32_dpp v79, v79, v79 quad_perm:[2,3,0,1] row_mask:0xf bank_mask:0xf bound_ctrl:1
	v_pk_mul_f32 v[88:89], v[72:73], v[142:143] op_sel:[0,1] op_sel_hi:[1,1]
	ds_read_b128 v[38:41], v100 offset:9472
	v_add_f32_dpp v78, v78, v78 row_half_mirror row_mask:0xf bank_mask:0xf bound_ctrl:1
	v_add_f32_dpp v79, v79, v79 row_half_mirror row_mask:0xf bank_mask:0xf bound_ctrl:1
	v_pk_fma_f32 v[82:83], v[2:3], v[136:137], v[82:83] op_sel_hi:[1,0,1]
	ds_read_b128 v[34:37], v100 offset:9216
	v_add_f32_dpp v78, v78, v78 row_mirror row_mask:0xf bank_mask:0xf bound_ctrl:1
	v_add_f32_dpp v79, v79, v79 row_mirror row_mask:0xf bank_mask:0xf bound_ctrl:1
	v_pk_fma_f32 v[84:85], v[4:5], v[136:137], v[84:85] op_sel:[0,1,0] op_sel_hi:[1,1,1]
	ds_read_b128 v[42:45], v100 offset:9728
	v_pk_fma_f32 v[86:87], v[6:7], v[138:139], v[86:87] op_sel_hi:[1,0,1]
	ds_read_b128 v[46:49], v100 offset:9984
	v_pk_fma_f32 v[88:89], v[8:9], v[138:139], v[88:89] op_sel:[0,1,0] op_sel_hi:[1,1,1]
	v_cndmask_b32_e64 v109, v95, v97, s[50:51]
	v_cndmask_b32_e64 v111, v97, v95, s[50:51]
	v_add_f32_dpp v112, v106, v104 quad_perm:[1,0,3,2] row_mask:0xf bank_mask:0xf bound_ctrl:1
	v_pk_fma_f32 v[2:3], v[78:79], v[144:145], v[82:83] op_sel_hi:[1,0,1]
	v_pk_fma_f32 v[4:5], v[78:79], v[144:145], v[84:85] op_sel:[0,1,0] op_sel_hi:[1,1,1]
	v_pk_fma_f32 v[6:7], v[78:79], v[146:147], v[86:87] op_sel_hi:[1,0,1]
	v_pk_fma_f32 v[8:9], v[78:79], v[146:147], v[88:89] op_sel:[0,1,0] op_sel_hi:[1,1,1]
	v_add_f32_dpp v114, v110, v108 quad_perm:[1,0,3,2] row_mask:0xf bank_mask:0xf bound_ctrl:1
	v_add_f32_dpp v113, v107, v105 quad_perm:[1,0,3,2] row_mask:0xf bank_mask:0xf bound_ctrl:1
	v_add_f32_dpp v115, v111, v109 quad_perm:[1,0,3,2] row_mask:0xf bank_mask:0xf bound_ctrl:1
	s_waitcnt lgkmcnt(5)
; #define LAS __attribute__((address_space(3)))
; __device__ __forceinline__ void phase_scan(CParams& P, LAS unsigned char* lds) {
;     ...
; #pragma unroll 2
;                 for (int j = 0; j < CH; j += 2) { const LAS float* sp = base + j * STEPF;
;                     SC_LOAD(B, sp + STEPF); SC_STEP(A);
;                     SC_LOAD(A, sp + 2 * STEPF);
;                     SC_STEP(B); }
	v_pk_mul_f32 v[78:79], v[2:3], v[10:11] op_sel_hi:[1,0]
	v_pk_mul_f32 v[92:93], v[2:3], v[148:149] op_sel_hi:[1,0]
	v_pk_fma_f32 v[78:79], v[4:5], v[10:11], v[78:79] op_sel:[0,1,0] op_sel_hi:[1,1,1]
	v_pk_fma_f32 v[92:93], v[4:5], v[148:149], v[92:93] op_sel:[0,1,0] op_sel_hi:[1,1,1]
	v_pk_fma_f32 v[78:79], v[6:7], v[12:13], v[78:79] op_sel_hi:[1,0,1]
	v_pk_fma_f32 v[92:93], v[6:7], v[150:151], v[92:93] op_sel_hi:[1,0,1]
	v_pk_fma_f32 v[78:79], v[8:9], v[12:13], v[78:79] op_sel:[0,1,0] op_sel_hi:[1,1,1]
	v_pk_mul_f32 v[82:83], v[74:75], v[18:19] op_sel_hi:[1,0]
	v_pk_fma_f32 v[92:93], v[8:9], v[150:151], v[92:93] op_sel:[0,1,0] op_sel_hi:[1,1,1]
	v_pk_mul_f32 v[84:85], v[74:75], v[18:19] op_sel:[0,1] op_sel_hi:[1,1]
	v_add_f32_dpp v78, v78, v78 quad_perm:[1,0,3,2] row_mask:0xf bank_mask:0xf bound_ctrl:1
	v_add_f32_dpp v79, v79, v79 quad_perm:[1,0,3,2] row_mask:0xf bank_mask:0xf bound_ctrl:1
	v_pk_mul_f32 v[86:87], v[74:75], v[20:21] op_sel_hi:[1,0]
	ds_read_b128 v[132:135], v100 offset:10240
	v_add_f32_dpp v78, v78, v78 quad_perm:[2,3,0,1] row_mask:0xf bank_mask:0xf bound_ctrl:1
	v_add_f32_dpp v79, v79, v79 quad_perm:[2,3,0,1] row_mask:0xf bank_mask:0xf bound_ctrl:1
	v_pk_mul_f32 v[88:89], v[74:75], v[20:21] op_sel:[0,1] op_sel_hi:[1,1]
	ds_read_b128 v[140:143], v100 offset:10752
	v_add_f32_dpp v78, v78, v78 row_half_mirror row_mask:0xf bank_mask:0xf bound_ctrl:1
	v_add_f32_dpp v79, v79, v79 row_half_mirror row_mask:0xf bank_mask:0xf bound_ctrl:1
	v_pk_fma_f32 v[82:83], v[2:3], v[14:15], v[82:83] op_sel_hi:[1,0,1]
	ds_read_b128 v[136:139], v100 offset:10496
	v_add_f32_dpp v78, v78, v78 row_mirror row_mask:0xf bank_mask:0xf bound_ctrl:1
	v_add_f32_dpp v79, v79, v79 row_mirror row_mask:0xf bank_mask:0xf bound_ctrl:1
	v_pk_fma_f32 v[84:85], v[4:5], v[14:15], v[84:85] op_sel:[0,1,0] op_sel_hi:[1,1,1]
	ds_read_b128 v[144:147], v100 offset:11008
	v_pk_fma_f32 v[86:87], v[6:7], v[16:17], v[86:87] op_sel_hi:[1,0,1]
	ds_read_b128 v[148:151], v100 offset:11264
	v_pk_fma_f32 v[88:89], v[8:9], v[16:17], v[88:89] op_sel:[0,1,0] op_sel_hi:[1,1,1]
	ds_read_b128 v[70:73], v101 offset:64
	v_cndmask_b32_e64 v116, v112, v114, s[52:53]
	v_cndmask_b32_e64 v118, v114, v112, s[52:53]
	v_cndmask_b32_e64 v117, v113, v115, s[52:53]
	v_pk_fma_f32 v[2:3], v[78:79], v[22:23], v[82:83] op_sel_hi:[1,0,1]
	v_pk_fma_f32 v[4:5], v[78:79], v[22:23], v[84:85] op_sel:[0,1,0] op_sel_hi:[1,1,1]
	v_pk_fma_f32 v[6:7], v[78:79], v[24:25], v[86:87] op_sel_hi:[1,0,1]
	v_pk_fma_f32 v[8:9], v[78:79], v[24:25], v[88:89] op_sel:[0,1,0] op_sel_hi:[1,1,1]
	v_cndmask_b32_e64 v119, v115, v113, s[52:53]
	v_add_f32_dpp v120, v118, v116 quad_perm:[2,3,0,1] row_mask:0xf bank_mask:0xf bound_ctrl:1
	s_nop 0
	v_add_f32_dpp v121, v119, v117 quad_perm:[2,3,0,1] row_mask:0xf bank_mask:0xf bound_ctrl:1
	s_waitcnt lgkmcnt(6)
	v_pk_mul_f32 v[78:79], v[2:3], v[30:31] op_sel_hi:[1,0]
	v_pk_mul_f32 v[94:95], v[2:3], v[26:27] op_sel_hi:[1,0]
	v_pk_fma_f32 v[78:79], v[4:5], v[30:31], v[78:79] op_sel:[0,1,0] op_sel_hi:[1,1,1]
	v_pk_fma_f32 v[94:95], v[4:5], v[26:27], v[94:95] op_sel:[0,1,0] op_sel_hi:[1,1,1]
	v_pk_fma_f32 v[78:79], v[6:7], v[32:33], v[78:79] op_sel_hi:[1,0,1]
	v_pk_fma_f32 v[94:95], v[6:7], v[28:29], v[94:95] op_sel_hi:[1,0,1]
	v_pk_fma_f32 v[78:79], v[8:9], v[32:33], v[78:79] op_sel:[0,1,0] op_sel_hi:[1,1,1]
	v_pk_mul_f32 v[82:83], v[76:77], v[38:39] op_sel_hi:[1,0]
	v_pk_fma_f32 v[94:95], v[8:9], v[28:29], v[94:95] op_sel:[0,1,0] op_sel_hi:[1,1,1]
	v_pk_mul_f32 v[84:85], v[76:77], v[38:39] op_sel:[0,1] op_sel_hi:[1,1]
	v_add_f32_dpp v78, v78, v78 quad_perm:[1,0,3,2] row_mask:0xf bank_mask:0xf bound_ctrl:1
	v_add_f32_dpp v79, v79, v79 quad_perm:[1,0,3,2] row_mask:0xf bank_mask:0xf bound_ctrl:1
	v_pk_mul_f32 v[86:87], v[76:77], v[40:41] op_sel_hi:[1,0]
	ds_read_b128 v[10:13], v100 offset:11520
	v_add_f32_dpp v78, v78, v78 quad_perm:[2,3,0,1] row_mask:0xf bank_mask:0xf bound_ctrl:1
	v_add_f32_dpp v79, v79, v79 quad_perm:[2,3,0,1] row_mask:0xf bank_mask:0xf bound_ctrl:1
	v_pk_mul_f32 v[88:89], v[76:77], v[40:41] op_sel:[0,1] op_sel_hi:[1,1]
	ds_read_b128 v[18:21], v100 offset:12032
	v_add_f32_dpp v78, v78, v78 row_half_mirror row_mask:0xf bank_mask:0xf bound_ctrl:1
	v_add_f32_dpp v79, v79, v79 row_half_mirror row_mask:0xf bank_mask:0xf bound_ctrl:1
	v_pk_fma_f32 v[82:83], v[2:3], v[34:35], v[82:83] op_sel_hi:[1,0,1]
	ds_read_b128 v[14:17], v100 offset:11776
	v_add_f32_dpp v78, v78, v78 row_mirror row_mask:0xf bank_mask:0xf bound_ctrl:1
	v_add_f32_dpp v79, v79, v79 row_mirror row_mask:0xf bank_mask:0xf bound_ctrl:1
	v_pk_fma_f32 v[84:85], v[4:5], v[34:35], v[84:85] op_sel:[0,1,0] op_sel_hi:[1,1,1]
	ds_read_b128 v[22:25], v100 offset:12288
	v_pk_fma_f32 v[86:87], v[6:7], v[36:37], v[86:87] op_sel_hi:[1,0,1]
	ds_read_b128 v[26:29], v100 offset:12544
	v_pk_fma_f32 v[88:89], v[8:9], v[36:37], v[88:89] op_sel:[0,1,0] op_sel_hi:[1,1,1]
	v_add_f32_dpp v120, v120, v120 row_ror:4 row_mask:0xf bank_mask:0xf bound_ctrl:1
	v_add_f32_dpp v121, v121, v121 row_ror:4 row_mask:0xf bank_mask:0xf bound_ctrl:1
	s_nop 0
	v_add_f32_dpp v120, v120, v120 row_ror:8 row_mask:0xf bank_mask:0xf bound_ctrl:1
	v_pk_fma_f32 v[2:3], v[78:79], v[42:43], v[82:83] op_sel_hi:[1,0,1]
	v_pk_fma_f32 v[4:5], v[78:79], v[42:43], v[84:85] op_sel:[0,1,0] op_sel_hi:[1,1,1]
	v_pk_fma_f32 v[6:7], v[78:79], v[44:45], v[86:87] op_sel_hi:[1,0,1]
	v_pk_fma_f32 v[8:9], v[78:79], v[44:45], v[88:89] op_sel:[0,1,0] op_sel_hi:[1,1,1]
	v_add_f32_dpp v121, v121, v121 row_ror:8 row_mask:0xf bank_mask:0xf bound_ctrl:1
	global_store_dwordx2 v102, v[120:121], s[10:11]
	v_add_u32_e32 v102, s13, v102
	s_waitcnt lgkmcnt(5)
; #define LAS __attribute__((address_space(3)))
; __device__ __forceinline__ void phase_scan(CParams& P, LAS unsigned char* lds) {
;     ...
; #pragma unroll 2
;                 for (int j = 0; j < CH; j += 2) { const LAS float* sp = base + j * STEPF;
;                     SC_LOAD(B, sp + STEPF); SC_STEP(A);
;                     SC_LOAD(A, sp + 2 * STEPF);
;                     SC_STEP(B); }
	v_pk_mul_f32 v[78:79], v[2:3], v[132:133] op_sel_hi:[1,0]
	v_pk_mul_f32 v[96:97], v[2:3], v[46:47] op_sel_hi:[1,0]
	v_pk_fma_f32 v[78:79], v[4:5], v[132:133], v[78:79] op_sel:[0,1,0] op_sel_hi:[1,1,1]
	v_pk_fma_f32 v[96:97], v[4:5], v[46:47], v[96:97] op_sel:[0,1,0] op_sel_hi:[1,1,1]
	v_pk_fma_f32 v[78:79], v[6:7], v[134:135], v[78:79] op_sel_hi:[1,0,1]
	v_pk_fma_f32 v[96:97], v[6:7], v[48:49], v[96:97] op_sel_hi:[1,0,1]
	v_pk_fma_f32 v[78:79], v[8:9], v[134:135], v[78:79] op_sel:[0,1,0] op_sel_hi:[1,1,1]
	v_pk_mul_f32 v[82:83], v[70:71], v[140:141] op_sel_hi:[1,0]
	v_pk_fma_f32 v[96:97], v[8:9], v[48:49], v[96:97] op_sel:[0,1,0] op_sel_hi:[1,1,1]
	v_pk_mul_f32 v[84:85], v[70:71], v[140:141] op_sel:[0,1] op_sel_hi:[1,1]
	v_add_f32_dpp v78, v78, v78 quad_perm:[1,0,3,2] row_mask:0xf bank_mask:0xf bound_ctrl:1
	v_add_f32_dpp v79, v79, v79 quad_perm:[1,0,3,2] row_mask:0xf bank_mask:0xf bound_ctrl:1
	v_pk_mul_f32 v[86:87], v[70:71], v[142:143] op_sel_hi:[1,0]
	ds_read_b128 v[30:33], v100 offset:12800
	v_add_f32_dpp v78, v78, v78 quad_perm:[2,3,0,1] row_mask:0xf bank_mask:0xf bound_ctrl:1
	v_add_f32_dpp v79, v79, v79 quad_perm:[2,3,0,1] row_mask:0xf bank_mask:0xf bound_ctrl:1
	v_pk_mul_f32 v[88:89], v[70:71], v[142:143] op_sel:[0,1] op_sel_hi:[1,1]
	ds_read_b128 v[38:41], v100 offset:13312
	v_add_f32_dpp v78, v78, v78 row_half_mirror row_mask:0xf bank_mask:0xf bound_ctrl:1
	v_add_f32_dpp v79, v79, v79 row_half_mirror row_mask:0xf bank_mask:0xf bound_ctrl:1
	v_pk_fma_f32 v[82:83], v[2:3], v[136:137], v[82:83] op_sel_hi:[1,0,1]
	ds_read_b128 v[34:37], v100 offset:13056
	v_add_f32_dpp v78, v78, v78 row_mirror row_mask:0xf bank_mask:0xf bound_ctrl:1
	v_add_f32_dpp v79, v79, v79 row_mirror row_mask:0xf bank_mask:0xf bound_ctrl:1
	v_pk_fma_f32 v[84:85], v[4:5], v[136:137], v[84:85] op_sel:[0,1,0] op_sel_hi:[1,1,1]
	ds_read_b128 v[42:45], v100 offset:13568
	v_pk_fma_f32 v[86:87], v[6:7], v[138:139], v[86:87] op_sel_hi:[1,0,1]
	ds_read_b128 v[46:49], v100 offset:13824
	v_pk_fma_f32 v[88:89], v[8:9], v[138:139], v[88:89] op_sel:[0,1,0] op_sel_hi:[1,1,1]
	ds_read_b128 v[74:77], v101 offset:80
	v_cndmask_b32_e64 v104, v90, v92, s[50:51]
	v_cndmask_b32_e64 v106, v92, v90, s[50:51]
	v_cndmask_b32_e64 v108, v94, v96, s[50:51]
	v_pk_fma_f32 v[2:3], v[78:79], v[144:145], v[82:83] op_sel_hi:[1,0,1]
	v_pk_fma_f32 v[4:5], v[78:79], v[144:145], v[84:85] op_sel:[0,1,0] op_sel_hi:[1,1,1]
	v_pk_fma_f32 v[6:7], v[78:79], v[146:147], v[86:87] op_sel_hi:[1,0,1]
	v_pk_fma_f32 v[8:9], v[78:79], v[146:147], v[88:89] op_sel:[0,1,0] op_sel_hi:[1,1,1]
	v_cndmask_b32_e64 v110, v96, v94, s[50:51]
	v_cndmask_b32_e64 v105, v91, v93, s[50:51]
	v_cndmask_b32_e64 v107, v93, v91, s[50:51]
	s_waitcnt lgkmcnt(6)
	v_pk_mul_f32 v[78:79], v[2:3], v[10:11] op_sel_hi:[1,0]
	v_pk_mul_f32 v[90:91], v[2:3], v[148:149] op_sel_hi:[1,0]
	v_pk_fma_f32 v[78:79], v[4:5], v[10:11], v[78:79] op_sel:[0,1,0] op_sel_hi:[1,1,1]
	v_pk_fma_f32 v[90:91], v[4:5], v[148:149], v[90:91] op_sel:[0,1,0] op_sel_hi:[1,1,1]
	v_pk_fma_f32 v[78:79], v[6:7], v[12:13], v[78:79] op_sel_hi:[1,0,1]
	v_pk_fma_f32 v[90:91], v[6:7], v[150:151], v[90:91] op_sel_hi:[1,0,1]
	v_pk_fma_f32 v[78:79], v[8:9], v[12:13], v[78:79] op_sel:[0,1,0] op_sel_hi:[1,1,1]
	v_pk_mul_f32 v[82:83], v[72:73], v[18:19] op_sel_hi:[1,0]
	v_pk_fma_f32 v[90:91], v[8:9], v[150:151], v[90:91] op_sel:[0,1,0] op_sel_hi:[1,1,1]
	v_pk_mul_f32 v[84:85], v[72:73], v[18:19] op_sel:[0,1] op_sel_hi:[1,1]
	v_add_f32_dpp v78, v78, v78 quad_perm:[1,0,3,2] row_mask:0xf bank_mask:0xf bound_ctrl:1
	v_add_f32_dpp v79, v79, v79 quad_perm:[1,0,3,2] row_mask:0xf bank_mask:0xf bound_ctrl:1
	v_pk_mul_f32 v[86:87], v[72:73], v[20:21] op_sel_hi:[1,0]
	ds_read_b128 v[132:135], v100 offset:14080
	v_add_f32_dpp v78, v78, v78 quad_perm:[2,3,0,1] row_mask:0xf bank_mask:0xf bound_ctrl:1
	v_add_f32_dpp v79, v79, v79 quad_perm:[2,3,0,1] row_mask:0xf bank_mask:0xf bound_ctrl:1
	v_pk_mul_f32 v[88:89], v[72:73], v[20:21] op_sel:[0,1] op_sel_hi:[1,1]
	ds_read_b128 v[140:143], v100 offset:14592
	v_add_f32_dpp v78, v78, v78 row_half_mirror row_mask:0xf bank_mask:0xf bound_ctrl:1
	v_add_f32_dpp v79, v79, v79 row_half_mirror row_mask:0xf bank_mask:0xf bound_ctrl:1
	v_pk_fma_f32 v[82:83], v[2:3], v[14:15], v[82:83] op_sel_hi:[1,0,1]
	ds_read_b128 v[136:139], v100 offset:14336
	v_add_f32_dpp v78, v78, v78 row_mirror row_mask:0xf bank_mask:0xf bound_ctrl:1
	v_add_f32_dpp v79, v79, v79 row_mirror row_mask:0xf bank_mask:0xf bound_ctrl:1
	v_pk_fma_f32 v[84:85], v[4:5], v[14:15], v[84:85] op_sel:[0,1,0] op_sel_hi:[1,1,1]
	ds_read_b128 v[144:147], v100 offset:14848
	v_pk_fma_f32 v[86:87], v[6:7], v[16:17], v[86:87] op_sel_hi:[1,0,1]
	ds_read_b128 v[148:151], v100 offset:15104
	v_pk_fma_f32 v[88:89], v[8:9], v[16:17], v[88:89] op_sel:[0,1,0] op_sel_hi:[1,1,1]
	v_cndmask_b32_e64 v109, v95, v97, s[50:51]
	v_cndmask_b32_e64 v111, v97, v95, s[50:51]
	v_add_f32_dpp v112, v106, v104 quad_perm:[1,0,3,2] row_mask:0xf bank_mask:0xf bound_ctrl:1
	v_pk_fma_f32 v[2:3], v[78:79], v[22:23], v[82:83] op_sel_hi:[1,0,1]
	v_pk_fma_f32 v[4:5], v[78:79], v[22:23], v[84:85] op_sel:[0,1,0] op_sel_hi:[1,1,1]
	v_pk_fma_f32 v[6:7], v[78:79], v[24:25], v[86:87] op_sel_hi:[1,0,1]
	v_pk_fma_f32 v[8:9], v[78:79], v[24:25], v[88:89] op_sel:[0,1,0] op_sel_hi:[1,1,1]
	v_add_f32_dpp v114, v110, v108 quad_perm:[1,0,3,2] row_mask:0xf bank_mask:0xf bound_ctrl:1
	v_add_f32_dpp v113, v107, v105 quad_perm:[1,0,3,2] row_mask:0xf bank_mask:0xf bound_ctrl:1
	v_add_f32_dpp v115, v111, v109 quad_perm:[1,0,3,2] row_mask:0xf bank_mask:0xf bound_ctrl:1
	s_waitcnt lgkmcnt(5)
; #define LAS __attribute__((address_space(3)))
; __device__ __forceinline__ void phase_scan(CParams& P, LAS unsigned char* lds) {
;     ...
; #pragma unroll 2
;                 for (int j = 0; j < CH; j += 2) { const LAS float* sp = base + j * STEPF;
;                     SC_LOAD(B, sp + STEPF); SC_STEP(A);
;                     SC_LOAD(A, sp + 2 * STEPF);
;                     SC_STEP(B); }
	v_pk_mul_f32 v[78:79], v[2:3], v[30:31] op_sel_hi:[1,0]
	v_pk_mul_f32 v[92:93], v[2:3], v[26:27] op_sel_hi:[1,0]
	v_pk_fma_f32 v[78:79], v[4:5], v[30:31], v[78:79] op_sel:[0,1,0] op_sel_hi:[1,1,1]
	v_pk_fma_f32 v[92:93], v[4:5], v[26:27], v[92:93] op_sel:[0,1,0] op_sel_hi:[1,1,1]
	v_pk_fma_f32 v[78:79], v[6:7], v[32:33], v[78:79] op_sel_hi:[1,0,1]
	v_pk_fma_f32 v[92:93], v[6:7], v[28:29], v[92:93] op_sel_hi:[1,0,1]
	v_pk_fma_f32 v[78:79], v[8:9], v[32:33], v[78:79] op_sel:[0,1,0] op_sel_hi:[1,1,1]
	v_pk_mul_f32 v[82:83], v[74:75], v[38:39] op_sel_hi:[1,0]
	v_pk_fma_f32 v[92:93], v[8:9], v[28:29], v[92:93] op_sel:[0,1,0] op_sel_hi:[1,1,1]
	v_pk_mul_f32 v[84:85], v[74:75], v[38:39] op_sel:[0,1] op_sel_hi:[1,1]
	v_add_f32_dpp v78, v78, v78 quad_perm:[1,0,3,2] row_mask:0xf bank_mask:0xf bound_ctrl:1
	v_add_f32_dpp v79, v79, v79 quad_perm:[1,0,3,2] row_mask:0xf bank_mask:0xf bound_ctrl:1
	v_pk_mul_f32 v[86:87], v[74:75], v[40:41] op_sel_hi:[1,0]
	ds_read_b128 v[10:13], v100 offset:15360
	v_add_f32_dpp v78, v78, v78 quad_perm:[2,3,0,1] row_mask:0xf bank_mask:0xf bound_ctrl:1
	v_add_f32_dpp v79, v79, v79 quad_perm:[2,3,0,1] row_mask:0xf bank_mask:0xf bound_ctrl:1
	v_pk_mul_f32 v[88:89], v[74:75], v[40:41] op_sel:[0,1] op_sel_hi:[1,1]
	ds_read_b128 v[18:21], v100 offset:15872
	v_add_f32_dpp v78, v78, v78 row_half_mirror row_mask:0xf bank_mask:0xf bound_ctrl:1
	v_add_f32_dpp v79, v79, v79 row_half_mirror row_mask:0xf bank_mask:0xf bound_ctrl:1
	v_pk_fma_f32 v[82:83], v[2:3], v[34:35], v[82:83] op_sel_hi:[1,0,1]
	ds_read_b128 v[14:17], v100 offset:15616
	v_add_f32_dpp v78, v78, v78 row_mirror row_mask:0xf bank_mask:0xf bound_ctrl:1
	v_add_f32_dpp v79, v79, v79 row_mirror row_mask:0xf bank_mask:0xf bound_ctrl:1
	v_pk_fma_f32 v[84:85], v[4:5], v[34:35], v[84:85] op_sel:[0,1,0] op_sel_hi:[1,1,1]
	ds_read_b128 v[22:25], v100 offset:16128
	v_pk_fma_f32 v[86:87], v[6:7], v[36:37], v[86:87] op_sel_hi:[1,0,1]
	ds_read_b128 v[26:29], v100 offset:16384
	v_pk_fma_f32 v[88:89], v[8:9], v[36:37], v[88:89] op_sel:[0,1,0] op_sel_hi:[1,1,1]
	ds_read_b128 v[70:73], v101 offset:96
	v_cndmask_b32_e64 v116, v112, v114, s[52:53]
	v_cndmask_b32_e64 v118, v114, v112, s[52:53]
	v_cndmask_b32_e64 v117, v113, v115, s[52:53]
	v_pk_fma_f32 v[2:3], v[78:79], v[42:43], v[82:83] op_sel_hi:[1,0,1]
	v_pk_fma_f32 v[4:5], v[78:79], v[42:43], v[84:85] op_sel:[0,1,0] op_sel_hi:[1,1,1]
	v_pk_fma_f32 v[6:7], v[78:79], v[44:45], v[86:87] op_sel_hi:[1,0,1]
	v_pk_fma_f32 v[8:9], v[78:79], v[44:45], v[88:89] op_sel:[0,1,0] op_sel_hi:[1,1,1]
	v_cndmask_b32_e64 v119, v115, v113, s[52:53]
	v_add_f32_dpp v120, v118, v116 quad_perm:[2,3,0,1] row_mask:0xf bank_mask:0xf bound_ctrl:1
	s_nop 0
	v_add_f32_dpp v121, v119, v117 quad_perm:[2,3,0,1] row_mask:0xf bank_mask:0xf bound_ctrl:1
	s_waitcnt lgkmcnt(6)
	v_pk_mul_f32 v[78:79], v[2:3], v[132:133] op_sel_hi:[1,0]
	v_pk_mul_f32 v[94:95], v[2:3], v[46:47] op_sel_hi:[1,0]
	v_pk_fma_f32 v[78:79], v[4:5], v[132:133], v[78:79] op_sel:[0,1,0] op_sel_hi:[1,1,1]
	v_pk_fma_f32 v[94:95], v[4:5], v[46:47], v[94:95] op_sel:[0,1,0] op_sel_hi:[1,1,1]
	v_pk_fma_f32 v[78:79], v[6:7], v[134:135], v[78:79] op_sel_hi:[1,0,1]
	v_pk_fma_f32 v[94:95], v[6:7], v[48:49], v[94:95] op_sel_hi:[1,0,1]
	v_pk_fma_f32 v[78:79], v[8:9], v[134:135], v[78:79] op_sel:[0,1,0] op_sel_hi:[1,1,1]
	v_pk_mul_f32 v[82:83], v[76:77], v[140:141] op_sel_hi:[1,0]
	v_pk_fma_f32 v[94:95], v[8:9], v[48:49], v[94:95] op_sel:[0,1,0] op_sel_hi:[1,1,1]
	v_pk_mul_f32 v[84:85], v[76:77], v[140:141] op_sel:[0,1] op_sel_hi:[1,1]
	v_add_f32_dpp v78, v78, v78 quad_perm:[1,0,3,2] row_mask:0xf bank_mask:0xf bound_ctrl:1
	v_add_f32_dpp v79, v79, v79 quad_perm:[1,0,3,2] row_mask:0xf bank_mask:0xf bound_ctrl:1
	v_pk_mul_f32 v[86:87], v[76:77], v[142:143] op_sel_hi:[1,0]
	ds_read_b128 v[30:33], v100 offset:16640
	v_add_f32_dpp v78, v78, v78 quad_perm:[2,3,0,1] row_mask:0xf bank_mask:0xf bound_ctrl:1
	v_add_f32_dpp v79, v79, v79 quad_perm:[2,3,0,1] row_mask:0xf bank_mask:0xf bound_ctrl:1
	v_pk_mul_f32 v[88:89], v[76:77], v[142:143] op_sel:[0,1] op_sel_hi:[1,1]
	ds_read_b128 v[38:41], v100 offset:17152
	v_add_f32_dpp v78, v78, v78 row_half_mirror row_mask:0xf bank_mask:0xf bound_ctrl:1
	v_add_f32_dpp v79, v79, v79 row_half_mirror row_mask:0xf bank_mask:0xf bound_ctrl:1
	v_pk_fma_f32 v[82:83], v[2:3], v[136:137], v[82:83] op_sel_hi:[1,0,1]
	ds_read_b128 v[34:37], v100 offset:16896
	v_add_f32_dpp v78, v78, v78 row_mirror row_mask:0xf bank_mask:0xf bound_ctrl:1
	v_add_f32_dpp v79, v79, v79 row_mirror row_mask:0xf bank_mask:0xf bound_ctrl:1
	v_pk_fma_f32 v[84:85], v[4:5], v[136:137], v[84:85] op_sel:[0,1,0] op_sel_hi:[1,1,1]
	ds_read_b128 v[42:45], v100 offset:17408
	v_pk_fma_f32 v[86:87], v[6:7], v[138:139], v[86:87] op_sel_hi:[1,0,1]
	ds_read_b128 v[46:49], v100 offset:17664
	v_pk_fma_f32 v[88:89], v[8:9], v[138:139], v[88:89] op_sel:[0,1,0] op_sel_hi:[1,1,1]
	v_add_f32_dpp v120, v120, v120 row_ror:4 row_mask:0xf bank_mask:0xf bound_ctrl:1
	v_add_f32_dpp v121, v121, v121 row_ror:4 row_mask:0xf bank_mask:0xf bound_ctrl:1
	s_nop 0
	v_add_f32_dpp v120, v120, v120 row_ror:8 row_mask:0xf bank_mask:0xf bound_ctrl:1
	v_pk_fma_f32 v[2:3], v[78:79], v[144:145], v[82:83] op_sel_hi:[1,0,1]
	v_pk_fma_f32 v[4:5], v[78:79], v[144:145], v[84:85] op_sel:[0,1,0] op_sel_hi:[1,1,1]
	v_pk_fma_f32 v[6:7], v[78:79], v[146:147], v[86:87] op_sel_hi:[1,0,1]
	v_pk_fma_f32 v[8:9], v[78:79], v[146:147], v[88:89] op_sel:[0,1,0] op_sel_hi:[1,1,1]
	v_add_f32_dpp v121, v121, v121 row_ror:8 row_mask:0xf bank_mask:0xf bound_ctrl:1
	global_store_dwordx2 v102, v[120:121], s[10:11]
	v_add_u32_e32 v102, s13, v102
	s_waitcnt lgkmcnt(5)
; #define LAS __attribute__((address_space(3)))
; __device__ __forceinline__ void phase_scan(CParams& P, LAS unsigned char* lds) {
;     ...
; #pragma unroll 2
;                 for (int j = 0; j < CH; j += 2) { const LAS float* sp = base + j * STEPF;
;                     SC_LOAD(B, sp + STEPF); SC_STEP(A);
;                     SC_LOAD(A, sp + 2 * STEPF);
;                     SC_STEP(B); }
	v_pk_mul_f32 v[78:79], v[2:3], v[10:11] op_sel_hi:[1,0]
	v_pk_mul_f32 v[96:97], v[2:3], v[148:149] op_sel_hi:[1,0]
	v_pk_fma_f32 v[78:79], v[4:5], v[10:11], v[78:79] op_sel:[0,1,0] op_sel_hi:[1,1,1]
	v_pk_fma_f32 v[96:97], v[4:5], v[148:149], v[96:97] op_sel:[0,1,0] op_sel_hi:[1,1,1]
	v_pk_fma_f32 v[78:79], v[6:7], v[12:13], v[78:79] op_sel_hi:[1,0,1]
	v_pk_fma_f32 v[96:97], v[6:7], v[150:151], v[96:97] op_sel_hi:[1,0,1]
	v_pk_fma_f32 v[78:79], v[8:9], v[12:13], v[78:79] op_sel:[0,1,0] op_sel_hi:[1,1,1]
	v_pk_mul_f32 v[82:83], v[70:71], v[18:19] op_sel_hi:[1,0]
	v_pk_fma_f32 v[96:97], v[8:9], v[150:151], v[96:97] op_sel:[0,1,0] op_sel_hi:[1,1,1]
	v_pk_mul_f32 v[84:85], v[70:71], v[18:19] op_sel:[0,1] op_sel_hi:[1,1]
	v_add_f32_dpp v78, v78, v78 quad_perm:[1,0,3,2] row_mask:0xf bank_mask:0xf bound_ctrl:1
	v_add_f32_dpp v79, v79, v79 quad_perm:[1,0,3,2] row_mask:0xf bank_mask:0xf bound_ctrl:1
	v_pk_mul_f32 v[86:87], v[70:71], v[20:21] op_sel_hi:[1,0]
	ds_read_b128 v[132:135], v100 offset:17920
	v_add_f32_dpp v78, v78, v78 quad_perm:[2,3,0,1] row_mask:0xf bank_mask:0xf bound_ctrl:1
	v_add_f32_dpp v79, v79, v79 quad_perm:[2,3,0,1] row_mask:0xf bank_mask:0xf bound_ctrl:1
	v_pk_mul_f32 v[88:89], v[70:71], v[20:21] op_sel:[0,1] op_sel_hi:[1,1]
	ds_read_b128 v[140:143], v100 offset:18432
	v_add_f32_dpp v78, v78, v78 row_half_mirror row_mask:0xf bank_mask:0xf bound_ctrl:1
	v_add_f32_dpp v79, v79, v79 row_half_mirror row_mask:0xf bank_mask:0xf bound_ctrl:1
	v_pk_fma_f32 v[82:83], v[2:3], v[14:15], v[82:83] op_sel_hi:[1,0,1]
	ds_read_b128 v[136:139], v100 offset:18176
	v_add_f32_dpp v78, v78, v78 row_mirror row_mask:0xf bank_mask:0xf bound_ctrl:1
	v_add_f32_dpp v79, v79, v79 row_mirror row_mask:0xf bank_mask:0xf bound_ctrl:1
	v_pk_fma_f32 v[84:85], v[4:5], v[14:15], v[84:85] op_sel:[0,1,0] op_sel_hi:[1,1,1]
	ds_read_b128 v[144:147], v100 offset:18688
	v_pk_fma_f32 v[86:87], v[6:7], v[16:17], v[86:87] op_sel_hi:[1,0,1]
	ds_read_b128 v[148:151], v100 offset:18944
	v_pk_fma_f32 v[88:89], v[8:9], v[16:17], v[88:89] op_sel:[0,1,0] op_sel_hi:[1,1,1]
	ds_read_b128 v[74:77], v101 offset:112
	v_cndmask_b32_e64 v104, v90, v92, s[50:51]
	v_cndmask_b32_e64 v106, v92, v90, s[50:51]
	v_cndmask_b32_e64 v108, v94, v96, s[50:51]
	v_pk_fma_f32 v[2:3], v[78:79], v[22:23], v[82:83] op_sel_hi:[1,0,1]
	v_pk_fma_f32 v[4:5], v[78:79], v[22:23], v[84:85] op_sel:[0,1,0] op_sel_hi:[1,1,1]
	v_pk_fma_f32 v[6:7], v[78:79], v[24:25], v[86:87] op_sel_hi:[1,0,1]
	v_pk_fma_f32 v[8:9], v[78:79], v[24:25], v[88:89] op_sel:[0,1,0] op_sel_hi:[1,1,1]
	v_cndmask_b32_e64 v110, v96, v94, s[50:51]
	v_cndmask_b32_e64 v105, v91, v93, s[50:51]
	v_cndmask_b32_e64 v107, v93, v91, s[50:51]
	s_waitcnt lgkmcnt(6)
	v_pk_mul_f32 v[78:79], v[2:3], v[30:31] op_sel_hi:[1,0]
	v_pk_mul_f32 v[90:91], v[2:3], v[26:27] op_sel_hi:[1,0]
	v_pk_fma_f32 v[78:79], v[4:5], v[30:31], v[78:79] op_sel:[0,1,0] op_sel_hi:[1,1,1]
	v_pk_fma_f32 v[90:91], v[4:5], v[26:27], v[90:91] op_sel:[0,1,0] op_sel_hi:[1,1,1]
	v_pk_fma_f32 v[78:79], v[6:7], v[32:33], v[78:79] op_sel_hi:[1,0,1]
	v_pk_fma_f32 v[90:91], v[6:7], v[28:29], v[90:91] op_sel_hi:[1,0,1]
	v_pk_fma_f32 v[78:79], v[8:9], v[32:33], v[78:79] op_sel:[0,1,0] op_sel_hi:[1,1,1]
	v_pk_mul_f32 v[82:83], v[72:73], v[38:39] op_sel_hi:[1,0]
	v_pk_fma_f32 v[90:91], v[8:9], v[28:29], v[90:91] op_sel:[0,1,0] op_sel_hi:[1,1,1]
	v_pk_mul_f32 v[84:85], v[72:73], v[38:39] op_sel:[0,1] op_sel_hi:[1,1]
	v_add_f32_dpp v78, v78, v78 quad_perm:[1,0,3,2] row_mask:0xf bank_mask:0xf bound_ctrl:1
	v_add_f32_dpp v79, v79, v79 quad_perm:[1,0,3,2] row_mask:0xf bank_mask:0xf bound_ctrl:1
	v_pk_mul_f32 v[86:87], v[72:73], v[40:41] op_sel_hi:[1,0]
	ds_read_b128 v[10:13], v100 offset:19200
	v_add_f32_dpp v78, v78, v78 quad_perm:[2,3,0,1] row_mask:0xf bank_mask:0xf bound_ctrl:1
	v_add_f32_dpp v79, v79, v79 quad_perm:[2,3,0,1] row_mask:0xf bank_mask:0xf bound_ctrl:1
	v_pk_mul_f32 v[88:89], v[72:73], v[40:41] op_sel:[0,1] op_sel_hi:[1,1]
	ds_read_b128 v[18:21], v100 offset:19712
	v_add_f32_dpp v78, v78, v78 row_half_mirror row_mask:0xf bank_mask:0xf bound_ctrl:1
	v_add_f32_dpp v79, v79, v79 row_half_mirror row_mask:0xf bank_mask:0xf bound_ctrl:1
	v_pk_fma_f32 v[82:83], v[2:3], v[34:35], v[82:83] op_sel_hi:[1,0,1]
	ds_read_b128 v[14:17], v100 offset:19456
	v_add_f32_dpp v78, v78, v78 row_mirror row_mask:0xf bank_mask:0xf bound_ctrl:1
	v_add_f32_dpp v79, v79, v79 row_mirror row_mask:0xf bank_mask:0xf bound_ctrl:1
	v_pk_fma_f32 v[84:85], v[4:5], v[34:35], v[84:85] op_sel:[0,1,0] op_sel_hi:[1,1,1]
	ds_read_b128 v[22:25], v100 offset:19968
	v_pk_fma_f32 v[86:87], v[6:7], v[36:37], v[86:87] op_sel_hi:[1,0,1]
	ds_read_b128 v[26:29], v100 offset:20224
	v_pk_fma_f32 v[88:89], v[8:9], v[36:37], v[88:89] op_sel:[0,1,0] op_sel_hi:[1,1,1]
	v_cndmask_b32_e64 v109, v95, v97, s[50:51]
	v_cndmask_b32_e64 v111, v97, v95, s[50:51]
	v_add_f32_dpp v112, v106, v104 quad_perm:[1,0,3,2] row_mask:0xf bank_mask:0xf bound_ctrl:1
	v_pk_fma_f32 v[2:3], v[78:79], v[42:43], v[82:83] op_sel_hi:[1,0,1]
	v_pk_fma_f32 v[4:5], v[78:79], v[42:43], v[84:85] op_sel:[0,1,0] op_sel_hi:[1,1,1]
	v_pk_fma_f32 v[6:7], v[78:79], v[44:45], v[86:87] op_sel_hi:[1,0,1]
	v_pk_fma_f32 v[8:9], v[78:79], v[44:45], v[88:89] op_sel:[0,1,0] op_sel_hi:[1,1,1]
	v_add_f32_dpp v114, v110, v108 quad_perm:[1,0,3,2] row_mask:0xf bank_mask:0xf bound_ctrl:1
	v_add_f32_dpp v113, v107, v105 quad_perm:[1,0,3,2] row_mask:0xf bank_mask:0xf bound_ctrl:1
	v_add_f32_dpp v115, v111, v109 quad_perm:[1,0,3,2] row_mask:0xf bank_mask:0xf bound_ctrl:1
	s_waitcnt lgkmcnt(5)
; #define LAS __attribute__((address_space(3)))
; __device__ __forceinline__ void phase_scan(CParams& P, LAS unsigned char* lds) {
;     ...
; #pragma unroll 2
;                 for (int j = 0; j < CH; j += 2) { const LAS float* sp = base + j * STEPF;
;                     SC_LOAD(B, sp + STEPF); SC_STEP(A);
;                     SC_LOAD(A, sp + 2 * STEPF);
;                     SC_STEP(B); }
	v_pk_mul_f32 v[78:79], v[2:3], v[132:133] op_sel_hi:[1,0]
	v_pk_mul_f32 v[92:93], v[2:3], v[46:47] op_sel_hi:[1,0]
	v_pk_fma_f32 v[78:79], v[4:5], v[132:133], v[78:79] op_sel:[0,1,0] op_sel_hi:[1,1,1]
	v_pk_fma_f32 v[92:93], v[4:5], v[46:47], v[92:93] op_sel:[0,1,0] op_sel_hi:[1,1,1]
	v_pk_fma_f32 v[78:79], v[6:7], v[134:135], v[78:79] op_sel_hi:[1,0,1]
	v_pk_fma_f32 v[92:93], v[6:7], v[48:49], v[92:93] op_sel_hi:[1,0,1]
	v_pk_fma_f32 v[78:79], v[8:9], v[134:135], v[78:79] op_sel:[0,1,0] op_sel_hi:[1,1,1]
	v_pk_mul_f32 v[82:83], v[74:75], v[140:141] op_sel_hi:[1,0]
	v_pk_fma_f32 v[92:93], v[8:9], v[48:49], v[92:93] op_sel:[0,1,0] op_sel_hi:[1,1,1]
	v_pk_mul_f32 v[84:85], v[74:75], v[140:141] op_sel:[0,1] op_sel_hi:[1,1]
	v_add_f32_dpp v78, v78, v78 quad_perm:[1,0,3,2] row_mask:0xf bank_mask:0xf bound_ctrl:1
	v_add_f32_dpp v79, v79, v79 quad_perm:[1,0,3,2] row_mask:0xf bank_mask:0xf bound_ctrl:1
	v_pk_mul_f32 v[86:87], v[74:75], v[142:143] op_sel_hi:[1,0]
	ds_read_b128 v[30:33], v100 offset:20480
	v_add_f32_dpp v78, v78, v78 quad_perm:[2,3,0,1] row_mask:0xf bank_mask:0xf bound_ctrl:1
	v_add_f32_dpp v79, v79, v79 quad_perm:[2,3,0,1] row_mask:0xf bank_mask:0xf bound_ctrl:1
	v_pk_mul_f32 v[88:89], v[74:75], v[142:143] op_sel:[0,1] op_sel_hi:[1,1]
	ds_read_b128 v[38:41], v100 offset:20992
	v_add_f32_dpp v78, v78, v78 row_half_mirror row_mask:0xf bank_mask:0xf bound_ctrl:1
	v_add_f32_dpp v79, v79, v79 row_half_mirror row_mask:0xf bank_mask:0xf bound_ctrl:1
	v_pk_fma_f32 v[82:83], v[2:3], v[136:137], v[82:83] op_sel_hi:[1,0,1]
	ds_read_b128 v[34:37], v100 offset:20736
	v_add_f32_dpp v78, v78, v78 row_mirror row_mask:0xf bank_mask:0xf bound_ctrl:1
	v_add_f32_dpp v79, v79, v79 row_mirror row_mask:0xf bank_mask:0xf bound_ctrl:1
	v_pk_fma_f32 v[84:85], v[4:5], v[136:137], v[84:85] op_sel:[0,1,0] op_sel_hi:[1,1,1]
	ds_read_b128 v[42:45], v100 offset:21248
	v_pk_fma_f32 v[86:87], v[6:7], v[138:139], v[86:87] op_sel_hi:[1,0,1]
	ds_read_b128 v[46:49], v100 offset:21504
	v_pk_fma_f32 v[88:89], v[8:9], v[138:139], v[88:89] op_sel:[0,1,0] op_sel_hi:[1,1,1]
	ds_read_b128 v[70:73], v101 offset:128
	v_cndmask_b32_e64 v116, v112, v114, s[52:53]
	v_cndmask_b32_e64 v118, v114, v112, s[52:53]
	v_cndmask_b32_e64 v117, v113, v115, s[52:53]
	v_pk_fma_f32 v[2:3], v[78:79], v[144:145], v[82:83] op_sel_hi:[1,0,1]
	v_pk_fma_f32 v[4:5], v[78:79], v[144:145], v[84:85] op_sel:[0,1,0] op_sel_hi:[1,1,1]
	v_pk_fma_f32 v[6:7], v[78:79], v[146:147], v[86:87] op_sel_hi:[1,0,1]
	v_pk_fma_f32 v[8:9], v[78:79], v[146:147], v[88:89] op_sel:[0,1,0] op_sel_hi:[1,1,1]
	v_cndmask_b32_e64 v119, v115, v113, s[52:53]
	v_add_f32_dpp v120, v118, v116 quad_perm:[2,3,0,1] row_mask:0xf bank_mask:0xf bound_ctrl:1
	s_nop 0
	v_add_f32_dpp v121, v119, v117 quad_perm:[2,3,0,1] row_mask:0xf bank_mask:0xf bound_ctrl:1
	s_waitcnt lgkmcnt(6)
	v_pk_mul_f32 v[78:79], v[2:3], v[10:11] op_sel_hi:[1,0]
	v_pk_mul_f32 v[94:95], v[2:3], v[148:149] op_sel_hi:[1,0]
	v_pk_fma_f32 v[78:79], v[4:5], v[10:11], v[78:79] op_sel:[0,1,0] op_sel_hi:[1,1,1]
	v_pk_fma_f32 v[94:95], v[4:5], v[148:149], v[94:95] op_sel:[0,1,0] op_sel_hi:[1,1,1]
	v_pk_fma_f32 v[78:79], v[6:7], v[12:13], v[78:79] op_sel_hi:[1,0,1]
	v_pk_fma_f32 v[94:95], v[6:7], v[150:151], v[94:95] op_sel_hi:[1,0,1]
	v_pk_fma_f32 v[78:79], v[8:9], v[12:13], v[78:79] op_sel:[0,1,0] op_sel_hi:[1,1,1]
	v_pk_mul_f32 v[82:83], v[76:77], v[18:19] op_sel_hi:[1,0]
	v_pk_fma_f32 v[94:95], v[8:9], v[150:151], v[94:95] op_sel:[0,1,0] op_sel_hi:[1,1,1]
	v_pk_mul_f32 v[84:85], v[76:77], v[18:19] op_sel:[0,1] op_sel_hi:[1,1]
	v_add_f32_dpp v78, v78, v78 quad_perm:[1,0,3,2] row_mask:0xf bank_mask:0xf bound_ctrl:1
	v_add_f32_dpp v79, v79, v79 quad_perm:[1,0,3,2] row_mask:0xf bank_mask:0xf bound_ctrl:1
	v_pk_mul_f32 v[86:87], v[76:77], v[20:21] op_sel_hi:[1,0]
	ds_read_b128 v[132:135], v100 offset:21760
	v_add_f32_dpp v78, v78, v78 quad_perm:[2,3,0,1] row_mask:0xf bank_mask:0xf bound_ctrl:1
	v_add_f32_dpp v79, v79, v79 quad_perm:[2,3,0,1] row_mask:0xf bank_mask:0xf bound_ctrl:1
	v_pk_mul_f32 v[88:89], v[76:77], v[20:21] op_sel:[0,1] op_sel_hi:[1,1]
	ds_read_b128 v[140:143], v100 offset:22272
	v_add_f32_dpp v78, v78, v78 row_half_mirror row_mask:0xf bank_mask:0xf bound_ctrl:1
	v_add_f32_dpp v79, v79, v79 row_half_mirror row_mask:0xf bank_mask:0xf bound_ctrl:1
	v_pk_fma_f32 v[82:83], v[2:3], v[14:15], v[82:83] op_sel_hi:[1,0,1]
	ds_read_b128 v[136:139], v100 offset:22016
	v_add_f32_dpp v78, v78, v78 row_mirror row_mask:0xf bank_mask:0xf bound_ctrl:1
	v_add_f32_dpp v79, v79, v79 row_mirror row_mask:0xf bank_mask:0xf bound_ctrl:1
	v_pk_fma_f32 v[84:85], v[4:5], v[14:15], v[84:85] op_sel:[0,1,0] op_sel_hi:[1,1,1]
	ds_read_b128 v[144:147], v100 offset:22528
	v_pk_fma_f32 v[86:87], v[6:7], v[16:17], v[86:87] op_sel_hi:[1,0,1]
	ds_read_b128 v[148:151], v100 offset:22784
	v_pk_fma_f32 v[88:89], v[8:9], v[16:17], v[88:89] op_sel:[0,1,0] op_sel_hi:[1,1,1]
	v_add_f32_dpp v120, v120, v120 row_ror:4 row_mask:0xf bank_mask:0xf bound_ctrl:1
	v_add_f32_dpp v121, v121, v121 row_ror:4 row_mask:0xf bank_mask:0xf bound_ctrl:1
	s_nop 0
	v_add_f32_dpp v120, v120, v120 row_ror:8 row_mask:0xf bank_mask:0xf bound_ctrl:1
	v_pk_fma_f32 v[2:3], v[78:79], v[22:23], v[82:83] op_sel_hi:[1,0,1]
	v_pk_fma_f32 v[4:5], v[78:79], v[22:23], v[84:85] op_sel:[0,1,0] op_sel_hi:[1,1,1]
	v_pk_fma_f32 v[6:7], v[78:79], v[24:25], v[86:87] op_sel_hi:[1,0,1]
	v_pk_fma_f32 v[8:9], v[78:79], v[24:25], v[88:89] op_sel:[0,1,0] op_sel_hi:[1,1,1]
	v_add_f32_dpp v121, v121, v121 row_ror:8 row_mask:0xf bank_mask:0xf bound_ctrl:1
	global_store_dwordx2 v102, v[120:121], s[10:11]
	v_add_u32_e32 v102, s13, v102
	s_waitcnt lgkmcnt(5)
; #define LAS __attribute__((address_space(3)))
; __device__ __forceinline__ void phase_scan(CParams& P, LAS unsigned char* lds) {
;     ...
; #pragma unroll 2
;                 for (int j = 0; j < CH; j += 2) { const LAS float* sp = base + j * STEPF;
;                     SC_LOAD(B, sp + STEPF); SC_STEP(A);
;                     SC_LOAD(A, sp + 2 * STEPF);
;                     SC_STEP(B); }
	v_pk_mul_f32 v[78:79], v[2:3], v[30:31] op_sel_hi:[1,0]
	v_pk_mul_f32 v[96:97], v[2:3], v[26:27] op_sel_hi:[1,0]
	v_pk_fma_f32 v[78:79], v[4:5], v[30:31], v[78:79] op_sel:[0,1,0] op_sel_hi:[1,1,1]
	v_pk_fma_f32 v[96:97], v[4:5], v[26:27], v[96:97] op_sel:[0,1,0] op_sel_hi:[1,1,1]
	v_pk_fma_f32 v[78:79], v[6:7], v[32:33], v[78:79] op_sel_hi:[1,0,1]
	v_pk_fma_f32 v[96:97], v[6:7], v[28:29], v[96:97] op_sel_hi:[1,0,1]
	v_pk_fma_f32 v[78:79], v[8:9], v[32:33], v[78:79] op_sel:[0,1,0] op_sel_hi:[1,1,1]
	v_pk_mul_f32 v[82:83], v[70:71], v[38:39] op_sel_hi:[1,0]
	v_pk_fma_f32 v[96:97], v[8:9], v[28:29], v[96:97] op_sel:[0,1,0] op_sel_hi:[1,1,1]
	v_pk_mul_f32 v[84:85], v[70:71], v[38:39] op_sel:[0,1] op_sel_hi:[1,1]
	v_add_f32_dpp v78, v78, v78 quad_perm:[1,0,3,2] row_mask:0xf bank_mask:0xf bound_ctrl:1
	v_add_f32_dpp v79, v79, v79 quad_perm:[1,0,3,2] row_mask:0xf bank_mask:0xf bound_ctrl:1
	v_pk_mul_f32 v[86:87], v[70:71], v[40:41] op_sel_hi:[1,0]
	ds_read_b128 v[10:13], v100 offset:23040
	v_add_f32_dpp v78, v78, v78 quad_perm:[2,3,0,1] row_mask:0xf bank_mask:0xf bound_ctrl:1
	v_add_f32_dpp v79, v79, v79 quad_perm:[2,3,0,1] row_mask:0xf bank_mask:0xf bound_ctrl:1
	v_pk_mul_f32 v[88:89], v[70:71], v[40:41] op_sel:[0,1] op_sel_hi:[1,1]
	ds_read_b128 v[18:21], v100 offset:23552
	v_add_f32_dpp v78, v78, v78 row_half_mirror row_mask:0xf bank_mask:0xf bound_ctrl:1
	v_add_f32_dpp v79, v79, v79 row_half_mirror row_mask:0xf bank_mask:0xf bound_ctrl:1
	v_pk_fma_f32 v[82:83], v[2:3], v[34:35], v[82:83] op_sel_hi:[1,0,1]
	ds_read_b128 v[14:17], v100 offset:23296
	v_add_f32_dpp v78, v78, v78 row_mirror row_mask:0xf bank_mask:0xf bound_ctrl:1
	v_add_f32_dpp v79, v79, v79 row_mirror row_mask:0xf bank_mask:0xf bound_ctrl:1
	v_pk_fma_f32 v[84:85], v[4:5], v[34:35], v[84:85] op_sel:[0,1,0] op_sel_hi:[1,1,1]
	ds_read_b128 v[22:25], v100 offset:23808
	v_pk_fma_f32 v[86:87], v[6:7], v[36:37], v[86:87] op_sel_hi:[1,0,1]
	ds_read_b128 v[26:29], v100 offset:24064
	v_pk_fma_f32 v[88:89], v[8:9], v[36:37], v[88:89] op_sel:[0,1,0] op_sel_hi:[1,1,1]
	ds_read_b128 v[74:77], v101 offset:144
	v_cndmask_b32_e64 v104, v90, v92, s[50:51]
	v_cndmask_b32_e64 v106, v92, v90, s[50:51]
	v_cndmask_b32_e64 v108, v94, v96, s[50:51]
	v_pk_fma_f32 v[2:3], v[78:79], v[42:43], v[82:83] op_sel_hi:[1,0,1]
	v_pk_fma_f32 v[4:5], v[78:79], v[42:43], v[84:85] op_sel:[0,1,0] op_sel_hi:[1,1,1]
	v_pk_fma_f32 v[6:7], v[78:79], v[44:45], v[86:87] op_sel_hi:[1,0,1]
	v_pk_fma_f32 v[8:9], v[78:79], v[44:45], v[88:89] op_sel:[0,1,0] op_sel_hi:[1,1,1]
	v_cndmask_b32_e64 v110, v96, v94, s[50:51]
	v_cndmask_b32_e64 v105, v91, v93, s[50:51]
	v_cndmask_b32_e64 v107, v93, v91, s[50:51]
	s_waitcnt lgkmcnt(6)
	v_pk_mul_f32 v[78:79], v[2:3], v[132:133] op_sel_hi:[1,0]
	v_pk_mul_f32 v[90:91], v[2:3], v[46:47] op_sel_hi:[1,0]
	v_pk_fma_f32 v[78:79], v[4:5], v[132:133], v[78:79] op_sel:[0,1,0] op_sel_hi:[1,1,1]
	v_pk_fma_f32 v[90:91], v[4:5], v[46:47], v[90:91] op_sel:[0,1,0] op_sel_hi:[1,1,1]
	v_pk_fma_f32 v[78:79], v[6:7], v[134:135], v[78:79] op_sel_hi:[1,0,1]
	v_pk_fma_f32 v[90:91], v[6:7], v[48:49], v[90:91] op_sel_hi:[1,0,1]
	v_pk_fma_f32 v[78:79], v[8:9], v[134:135], v[78:79] op_sel:[0,1,0] op_sel_hi:[1,1,1]
	v_pk_mul_f32 v[82:83], v[72:73], v[140:141] op_sel_hi:[1,0]
	v_pk_fma_f32 v[90:91], v[8:9], v[48:49], v[90:91] op_sel:[0,1,0] op_sel_hi:[1,1,1]
	v_pk_mul_f32 v[84:85], v[72:73], v[140:141] op_sel:[0,1] op_sel_hi:[1,1]
	v_add_f32_dpp v78, v78, v78 quad_perm:[1,0,3,2] row_mask:0xf bank_mask:0xf bound_ctrl:1
	v_add_f32_dpp v79, v79, v79 quad_perm:[1,0,3,2] row_mask:0xf bank_mask:0xf bound_ctrl:1
	v_pk_mul_f32 v[86:87], v[72:73], v[142:143] op_sel_hi:[1,0]
	ds_read_b128 v[30:33], v100 offset:24320
	v_add_f32_dpp v78, v78, v78 quad_perm:[2,3,0,1] row_mask:0xf bank_mask:0xf bound_ctrl:1
	v_add_f32_dpp v79, v79, v79 quad_perm:[2,3,0,1] row_mask:0xf bank_mask:0xf bound_ctrl:1
	v_pk_mul_f32 v[88:89], v[72:73], v[142:143] op_sel:[0,1] op_sel_hi:[1,1]
	ds_read_b128 v[38:41], v100 offset:24832
	v_add_f32_dpp v78, v78, v78 row_half_mirror row_mask:0xf bank_mask:0xf bound_ctrl:1
	v_add_f32_dpp v79, v79, v79 row_half_mirror row_mask:0xf bank_mask:0xf bound_ctrl:1
	v_pk_fma_f32 v[82:83], v[2:3], v[136:137], v[82:83] op_sel_hi:[1,0,1]
	ds_read_b128 v[34:37], v100 offset:24576
	v_add_f32_dpp v78, v78, v78 row_mirror row_mask:0xf bank_mask:0xf bound_ctrl:1
	v_add_f32_dpp v79, v79, v79 row_mirror row_mask:0xf bank_mask:0xf bound_ctrl:1
	v_pk_fma_f32 v[84:85], v[4:5], v[136:137], v[84:85] op_sel:[0,1,0] op_sel_hi:[1,1,1]
	ds_read_b128 v[42:45], v100 offset:25088
	v_pk_fma_f32 v[86:87], v[6:7], v[138:139], v[86:87] op_sel_hi:[1,0,1]
	ds_read_b128 v[46:49], v100 offset:25344
	v_pk_fma_f32 v[88:89], v[8:9], v[138:139], v[88:89] op_sel:[0,1,0] op_sel_hi:[1,1,1]
	v_cndmask_b32_e64 v109, v95, v97, s[50:51]
	v_cndmask_b32_e64 v111, v97, v95, s[50:51]
	v_add_f32_dpp v112, v106, v104 quad_perm:[1,0,3,2] row_mask:0xf bank_mask:0xf bound_ctrl:1
	v_pk_fma_f32 v[2:3], v[78:79], v[144:145], v[82:83] op_sel_hi:[1,0,1]
	v_pk_fma_f32 v[4:5], v[78:79], v[144:145], v[84:85] op_sel:[0,1,0] op_sel_hi:[1,1,1]
	v_pk_fma_f32 v[6:7], v[78:79], v[146:147], v[86:87] op_sel_hi:[1,0,1]
	v_pk_fma_f32 v[8:9], v[78:79], v[146:147], v[88:89] op_sel:[0,1,0] op_sel_hi:[1,1,1]
	v_add_f32_dpp v114, v110, v108 quad_perm:[1,0,3,2] row_mask:0xf bank_mask:0xf bound_ctrl:1
	v_add_f32_dpp v113, v107, v105 quad_perm:[1,0,3,2] row_mask:0xf bank_mask:0xf bound_ctrl:1
	v_add_f32_dpp v115, v111, v109 quad_perm:[1,0,3,2] row_mask:0xf bank_mask:0xf bound_ctrl:1
	s_waitcnt lgkmcnt(5)
; #define LAS __attribute__((address_space(3)))
; __device__ __forceinline__ void phase_scan(CParams& P, LAS unsigned char* lds) {
;     ...
; #pragma unroll 2
;                 for (int j = 0; j < CH; j += 2) { const LAS float* sp = base + j * STEPF;
;                     SC_LOAD(B, sp + STEPF); SC_STEP(A);
;                     SC_LOAD(A, sp + 2 * STEPF);
;                     SC_STEP(B); }
	v_pk_mul_f32 v[78:79], v[2:3], v[10:11] op_sel_hi:[1,0]
	v_pk_mul_f32 v[92:93], v[2:3], v[148:149] op_sel_hi:[1,0]
	v_pk_fma_f32 v[78:79], v[4:5], v[10:11], v[78:79] op_sel:[0,1,0] op_sel_hi:[1,1,1]
	v_pk_fma_f32 v[92:93], v[4:5], v[148:149], v[92:93] op_sel:[0,1,0] op_sel_hi:[1,1,1]
	v_pk_fma_f32 v[78:79], v[6:7], v[12:13], v[78:79] op_sel_hi:[1,0,1]
	v_pk_fma_f32 v[92:93], v[6:7], v[150:151], v[92:93] op_sel_hi:[1,0,1]
	v_pk_fma_f32 v[78:79], v[8:9], v[12:13], v[78:79] op_sel:[0,1,0] op_sel_hi:[1,1,1]
	v_pk_mul_f32 v[82:83], v[74:75], v[18:19] op_sel_hi:[1,0]
	v_pk_fma_f32 v[92:93], v[8:9], v[150:151], v[92:93] op_sel:[0,1,0] op_sel_hi:[1,1,1]
	v_pk_mul_f32 v[84:85], v[74:75], v[18:19] op_sel:[0,1] op_sel_hi:[1,1]
	v_add_f32_dpp v78, v78, v78 quad_perm:[1,0,3,2] row_mask:0xf bank_mask:0xf bound_ctrl:1
	v_add_f32_dpp v79, v79, v79 quad_perm:[1,0,3,2] row_mask:0xf bank_mask:0xf bound_ctrl:1
	v_pk_mul_f32 v[86:87], v[74:75], v[20:21] op_sel_hi:[1,0]
	ds_read_b128 v[132:135], v100 offset:25600
	v_add_f32_dpp v78, v78, v78 quad_perm:[2,3,0,1] row_mask:0xf bank_mask:0xf bound_ctrl:1
	v_add_f32_dpp v79, v79, v79 quad_perm:[2,3,0,1] row_mask:0xf bank_mask:0xf bound_ctrl:1
	v_pk_mul_f32 v[88:89], v[74:75], v[20:21] op_sel:[0,1] op_sel_hi:[1,1]
	ds_read_b128 v[140:143], v100 offset:26112
	v_add_f32_dpp v78, v78, v78 row_half_mirror row_mask:0xf bank_mask:0xf bound_ctrl:1
	v_add_f32_dpp v79, v79, v79 row_half_mirror row_mask:0xf bank_mask:0xf bound_ctrl:1
	v_pk_fma_f32 v[82:83], v[2:3], v[14:15], v[82:83] op_sel_hi:[1,0,1]
	ds_read_b128 v[136:139], v100 offset:25856
	v_add_f32_dpp v78, v78, v78 row_mirror row_mask:0xf bank_mask:0xf bound_ctrl:1
	v_add_f32_dpp v79, v79, v79 row_mirror row_mask:0xf bank_mask:0xf bound_ctrl:1
	v_pk_fma_f32 v[84:85], v[4:5], v[14:15], v[84:85] op_sel:[0,1,0] op_sel_hi:[1,1,1]
	ds_read_b128 v[144:147], v100 offset:26368
	v_pk_fma_f32 v[86:87], v[6:7], v[16:17], v[86:87] op_sel_hi:[1,0,1]
	ds_read_b128 v[148:151], v100 offset:26624
	v_pk_fma_f32 v[88:89], v[8:9], v[16:17], v[88:89] op_sel:[0,1,0] op_sel_hi:[1,1,1]
	ds_read_b128 v[70:73], v101 offset:160
	v_cndmask_b32_e64 v116, v112, v114, s[52:53]
	v_cndmask_b32_e64 v118, v114, v112, s[52:53]
	v_cndmask_b32_e64 v117, v113, v115, s[52:53]
	v_pk_fma_f32 v[2:3], v[78:79], v[22:23], v[82:83] op_sel_hi:[1,0,1]
	v_pk_fma_f32 v[4:5], v[78:79], v[22:23], v[84:85] op_sel:[0,1,0] op_sel_hi:[1,1,1]
	v_pk_fma_f32 v[6:7], v[78:79], v[24:25], v[86:87] op_sel_hi:[1,0,1]
	v_pk_fma_f32 v[8:9], v[78:79], v[24:25], v[88:89] op_sel:[0,1,0] op_sel_hi:[1,1,1]
	v_cndmask_b32_e64 v119, v115, v113, s[52:53]
	v_add_f32_dpp v120, v118, v116 quad_perm:[2,3,0,1] row_mask:0xf bank_mask:0xf bound_ctrl:1
	s_nop 0
	v_add_f32_dpp v121, v119, v117 quad_perm:[2,3,0,1] row_mask:0xf bank_mask:0xf bound_ctrl:1
	s_waitcnt lgkmcnt(6)
	v_pk_mul_f32 v[78:79], v[2:3], v[30:31] op_sel_hi:[1,0]
	v_pk_mul_f32 v[94:95], v[2:3], v[26:27] op_sel_hi:[1,0]
	v_pk_fma_f32 v[78:79], v[4:5], v[30:31], v[78:79] op_sel:[0,1,0] op_sel_hi:[1,1,1]
	v_pk_fma_f32 v[94:95], v[4:5], v[26:27], v[94:95] op_sel:[0,1,0] op_sel_hi:[1,1,1]
	v_pk_fma_f32 v[78:79], v[6:7], v[32:33], v[78:79] op_sel_hi:[1,0,1]
	v_pk_fma_f32 v[94:95], v[6:7], v[28:29], v[94:95] op_sel_hi:[1,0,1]
	v_pk_fma_f32 v[78:79], v[8:9], v[32:33], v[78:79] op_sel:[0,1,0] op_sel_hi:[1,1,1]
	v_pk_mul_f32 v[82:83], v[76:77], v[38:39] op_sel_hi:[1,0]
	v_pk_fma_f32 v[94:95], v[8:9], v[28:29], v[94:95] op_sel:[0,1,0] op_sel_hi:[1,1,1]
	v_pk_mul_f32 v[84:85], v[76:77], v[38:39] op_sel:[0,1] op_sel_hi:[1,1]
	v_add_f32_dpp v78, v78, v78 quad_perm:[1,0,3,2] row_mask:0xf bank_mask:0xf bound_ctrl:1
	v_add_f32_dpp v79, v79, v79 quad_perm:[1,0,3,2] row_mask:0xf bank_mask:0xf bound_ctrl:1
	v_pk_mul_f32 v[86:87], v[76:77], v[40:41] op_sel_hi:[1,0]
	ds_read_b128 v[10:13], v100 offset:26880
	v_add_f32_dpp v78, v78, v78 quad_perm:[2,3,0,1] row_mask:0xf bank_mask:0xf bound_ctrl:1
	v_add_f32_dpp v79, v79, v79 quad_perm:[2,3,0,1] row_mask:0xf bank_mask:0xf bound_ctrl:1
	v_pk_mul_f32 v[88:89], v[76:77], v[40:41] op_sel:[0,1] op_sel_hi:[1,1]
	ds_read_b128 v[18:21], v100 offset:27392
	v_add_f32_dpp v78, v78, v78 row_half_mirror row_mask:0xf bank_mask:0xf bound_ctrl:1
	v_add_f32_dpp v79, v79, v79 row_half_mirror row_mask:0xf bank_mask:0xf bound_ctrl:1
	v_pk_fma_f32 v[82:83], v[2:3], v[34:35], v[82:83] op_sel_hi:[1,0,1]
	ds_read_b128 v[14:17], v100 offset:27136
	v_add_f32_dpp v78, v78, v78 row_mirror row_mask:0xf bank_mask:0xf bound_ctrl:1
	v_add_f32_dpp v79, v79, v79 row_mirror row_mask:0xf bank_mask:0xf bound_ctrl:1
	v_pk_fma_f32 v[84:85], v[4:5], v[34:35], v[84:85] op_sel:[0,1,0] op_sel_hi:[1,1,1]
	ds_read_b128 v[22:25], v100 offset:27648
	v_pk_fma_f32 v[86:87], v[6:7], v[36:37], v[86:87] op_sel_hi:[1,0,1]
	ds_read_b128 v[26:29], v100 offset:27904
	v_pk_fma_f32 v[88:89], v[8:9], v[36:37], v[88:89] op_sel:[0,1,0] op_sel_hi:[1,1,1]
	v_add_f32_dpp v120, v120, v120 row_ror:4 row_mask:0xf bank_mask:0xf bound_ctrl:1
	v_add_f32_dpp v121, v121, v121 row_ror:4 row_mask:0xf bank_mask:0xf bound_ctrl:1
	s_nop 0
	v_add_f32_dpp v120, v120, v120 row_ror:8 row_mask:0xf bank_mask:0xf bound_ctrl:1
	v_pk_fma_f32 v[2:3], v[78:79], v[42:43], v[82:83] op_sel_hi:[1,0,1]
	v_pk_fma_f32 v[4:5], v[78:79], v[42:43], v[84:85] op_sel:[0,1,0] op_sel_hi:[1,1,1]
	v_pk_fma_f32 v[6:7], v[78:79], v[44:45], v[86:87] op_sel_hi:[1,0,1]
	v_pk_fma_f32 v[8:9], v[78:79], v[44:45], v[88:89] op_sel:[0,1,0] op_sel_hi:[1,1,1]
	v_add_f32_dpp v121, v121, v121 row_ror:8 row_mask:0xf bank_mask:0xf bound_ctrl:1
	global_store_dwordx2 v102, v[120:121], s[10:11]
	v_add_u32_e32 v102, s13, v102
	s_waitcnt lgkmcnt(5)
; #define LAS __attribute__((address_space(3)))
; __device__ __forceinline__ void phase_scan(CParams& P, LAS unsigned char* lds) {
;     ...
; #pragma unroll 2
;                 for (int j = 0; j < CH; j += 2) { const LAS float* sp = base + j * STEPF;
;                     SC_LOAD(B, sp + STEPF); SC_STEP(A);
;                     SC_LOAD(A, sp + 2 * STEPF);
;                     SC_STEP(B); }
	v_pk_mul_f32 v[78:79], v[2:3], v[132:133] op_sel_hi:[1,0]
	v_pk_mul_f32 v[96:97], v[2:3], v[46:47] op_sel_hi:[1,0]
	v_pk_fma_f32 v[78:79], v[4:5], v[132:133], v[78:79] op_sel:[0,1,0] op_sel_hi:[1,1,1]
	v_pk_fma_f32 v[96:97], v[4:5], v[46:47], v[96:97] op_sel:[0,1,0] op_sel_hi:[1,1,1]
	v_pk_fma_f32 v[78:79], v[6:7], v[134:135], v[78:79] op_sel_hi:[1,0,1]
	v_pk_fma_f32 v[96:97], v[6:7], v[48:49], v[96:97] op_sel_hi:[1,0,1]
	v_pk_fma_f32 v[78:79], v[8:9], v[134:135], v[78:79] op_sel:[0,1,0] op_sel_hi:[1,1,1]
	v_pk_mul_f32 v[82:83], v[70:71], v[140:141] op_sel_hi:[1,0]
	v_pk_fma_f32 v[96:97], v[8:9], v[48:49], v[96:97] op_sel:[0,1,0] op_sel_hi:[1,1,1]
	v_pk_mul_f32 v[84:85], v[70:71], v[140:141] op_sel:[0,1] op_sel_hi:[1,1]
	v_add_f32_dpp v78, v78, v78 quad_perm:[1,0,3,2] row_mask:0xf bank_mask:0xf bound_ctrl:1
	v_add_f32_dpp v79, v79, v79 quad_perm:[1,0,3,2] row_mask:0xf bank_mask:0xf bound_ctrl:1
	v_pk_mul_f32 v[86:87], v[70:71], v[142:143] op_sel_hi:[1,0]
	ds_read_b128 v[30:33], v100 offset:28160
	v_add_f32_dpp v78, v78, v78 quad_perm:[2,3,0,1] row_mask:0xf bank_mask:0xf bound_ctrl:1
	v_add_f32_dpp v79, v79, v79 quad_perm:[2,3,0,1] row_mask:0xf bank_mask:0xf bound_ctrl:1
	v_pk_mul_f32 v[88:89], v[70:71], v[142:143] op_sel:[0,1] op_sel_hi:[1,1]
	ds_read_b128 v[38:41], v100 offset:28672
	v_add_f32_dpp v78, v78, v78 row_half_mirror row_mask:0xf bank_mask:0xf bound_ctrl:1
	v_add_f32_dpp v79, v79, v79 row_half_mirror row_mask:0xf bank_mask:0xf bound_ctrl:1
	v_pk_fma_f32 v[82:83], v[2:3], v[136:137], v[82:83] op_sel_hi:[1,0,1]
	ds_read_b128 v[34:37], v100 offset:28416
	v_add_f32_dpp v78, v78, v78 row_mirror row_mask:0xf bank_mask:0xf bound_ctrl:1
	v_add_f32_dpp v79, v79, v79 row_mirror row_mask:0xf bank_mask:0xf bound_ctrl:1
	v_pk_fma_f32 v[84:85], v[4:5], v[136:137], v[84:85] op_sel:[0,1,0] op_sel_hi:[1,1,1]
	ds_read_b128 v[42:45], v100 offset:28928
	v_pk_fma_f32 v[86:87], v[6:7], v[138:139], v[86:87] op_sel_hi:[1,0,1]
	ds_read_b128 v[46:49], v100 offset:29184
	v_pk_fma_f32 v[88:89], v[8:9], v[138:139], v[88:89] op_sel:[0,1,0] op_sel_hi:[1,1,1]
	ds_read_b128 v[74:77], v101 offset:176
	v_cndmask_b32_e64 v104, v90, v92, s[50:51]
	v_cndmask_b32_e64 v106, v92, v90, s[50:51]
	v_cndmask_b32_e64 v108, v94, v96, s[50:51]
	v_pk_fma_f32 v[2:3], v[78:79], v[144:145], v[82:83] op_sel_hi:[1,0,1]
	v_pk_fma_f32 v[4:5], v[78:79], v[144:145], v[84:85] op_sel:[0,1,0] op_sel_hi:[1,1,1]
	v_pk_fma_f32 v[6:7], v[78:79], v[146:147], v[86:87] op_sel_hi:[1,0,1]
	v_pk_fma_f32 v[8:9], v[78:79], v[146:147], v[88:89] op_sel:[0,1,0] op_sel_hi:[1,1,1]
	v_cndmask_b32_e64 v110, v96, v94, s[50:51]
	v_cndmask_b32_e64 v105, v91, v93, s[50:51]
	v_cndmask_b32_e64 v107, v93, v91, s[50:51]
	s_waitcnt lgkmcnt(6)
	v_pk_mul_f32 v[78:79], v[2:3], v[10:11] op_sel_hi:[1,0]
	v_pk_mul_f32 v[90:91], v[2:3], v[148:149] op_sel_hi:[1,0]
	v_pk_fma_f32 v[78:79], v[4:5], v[10:11], v[78:79] op_sel:[0,1,0] op_sel_hi:[1,1,1]
	v_pk_fma_f32 v[90:91], v[4:5], v[148:149], v[90:91] op_sel:[0,1,0] op_sel_hi:[1,1,1]
	v_pk_fma_f32 v[78:79], v[6:7], v[12:13], v[78:79] op_sel_hi:[1,0,1]
	v_pk_fma_f32 v[90:91], v[6:7], v[150:151], v[90:91] op_sel_hi:[1,0,1]
	v_pk_fma_f32 v[78:79], v[8:9], v[12:13], v[78:79] op_sel:[0,1,0] op_sel_hi:[1,1,1]
	v_pk_mul_f32 v[82:83], v[72:73], v[18:19] op_sel_hi:[1,0]
	v_pk_fma_f32 v[90:91], v[8:9], v[150:151], v[90:91] op_sel:[0,1,0] op_sel_hi:[1,1,1]
	v_pk_mul_f32 v[84:85], v[72:73], v[18:19] op_sel:[0,1] op_sel_hi:[1,1]
	v_add_f32_dpp v78, v78, v78 quad_perm:[1,0,3,2] row_mask:0xf bank_mask:0xf bound_ctrl:1
	v_add_f32_dpp v79, v79, v79 quad_perm:[1,0,3,2] row_mask:0xf bank_mask:0xf bound_ctrl:1
	v_pk_mul_f32 v[86:87], v[72:73], v[20:21] op_sel_hi:[1,0]
	ds_read_b128 v[132:135], v100 offset:29440
	v_add_f32_dpp v78, v78, v78 quad_perm:[2,3,0,1] row_mask:0xf bank_mask:0xf bound_ctrl:1
	v_add_f32_dpp v79, v79, v79 quad_perm:[2,3,0,1] row_mask:0xf bank_mask:0xf bound_ctrl:1
	v_pk_mul_f32 v[88:89], v[72:73], v[20:21] op_sel:[0,1] op_sel_hi:[1,1]
	ds_read_b128 v[140:143], v100 offset:29952
	v_add_f32_dpp v78, v78, v78 row_half_mirror row_mask:0xf bank_mask:0xf bound_ctrl:1
	v_add_f32_dpp v79, v79, v79 row_half_mirror row_mask:0xf bank_mask:0xf bound_ctrl:1
	v_pk_fma_f32 v[82:83], v[2:3], v[14:15], v[82:83] op_sel_hi:[1,0,1]
	ds_read_b128 v[136:139], v100 offset:29696
	v_add_f32_dpp v78, v78, v78 row_mirror row_mask:0xf bank_mask:0xf bound_ctrl:1
	v_add_f32_dpp v79, v79, v79 row_mirror row_mask:0xf bank_mask:0xf bound_ctrl:1
	v_pk_fma_f32 v[84:85], v[4:5], v[14:15], v[84:85] op_sel:[0,1,0] op_sel_hi:[1,1,1]
	ds_read_b128 v[144:147], v100 offset:30208
	v_pk_fma_f32 v[86:87], v[6:7], v[16:17], v[86:87] op_sel_hi:[1,0,1]
	ds_read_b128 v[148:151], v100 offset:30464
	v_pk_fma_f32 v[88:89], v[8:9], v[16:17], v[88:89] op_sel:[0,1,0] op_sel_hi:[1,1,1]
	v_cndmask_b32_e64 v109, v95, v97, s[50:51]
	v_cndmask_b32_e64 v111, v97, v95, s[50:51]
	v_add_f32_dpp v112, v106, v104 quad_perm:[1,0,3,2] row_mask:0xf bank_mask:0xf bound_ctrl:1
	v_pk_fma_f32 v[2:3], v[78:79], v[22:23], v[82:83] op_sel_hi:[1,0,1]
	v_pk_fma_f32 v[4:5], v[78:79], v[22:23], v[84:85] op_sel:[0,1,0] op_sel_hi:[1,1,1]
	v_pk_fma_f32 v[6:7], v[78:79], v[24:25], v[86:87] op_sel_hi:[1,0,1]
	v_pk_fma_f32 v[8:9], v[78:79], v[24:25], v[88:89] op_sel:[0,1,0] op_sel_hi:[1,1,1]
	v_add_f32_dpp v114, v110, v108 quad_perm:[1,0,3,2] row_mask:0xf bank_mask:0xf bound_ctrl:1
	v_add_f32_dpp v113, v107, v105 quad_perm:[1,0,3,2] row_mask:0xf bank_mask:0xf bound_ctrl:1
	v_add_f32_dpp v115, v111, v109 quad_perm:[1,0,3,2] row_mask:0xf bank_mask:0xf bound_ctrl:1
	s_waitcnt lgkmcnt(5)
; #define LAS __attribute__((address_space(3)))
; __device__ __forceinline__ void phase_scan(CParams& P, LAS unsigned char* lds) {
;     ...
; #pragma unroll 2
;                 for (int j = 0; j < CH; j += 2) { const LAS float* sp = base + j * STEPF;
;                     SC_LOAD(B, sp + STEPF); SC_STEP(A);
;                     SC_LOAD(A, sp + 2 * STEPF);
;                     SC_STEP(B); }
	v_pk_mul_f32 v[78:79], v[2:3], v[30:31] op_sel_hi:[1,0]
	v_pk_mul_f32 v[92:93], v[2:3], v[26:27] op_sel_hi:[1,0]
	v_pk_fma_f32 v[78:79], v[4:5], v[30:31], v[78:79] op_sel:[0,1,0] op_sel_hi:[1,1,1]
	v_pk_fma_f32 v[92:93], v[4:5], v[26:27], v[92:93] op_sel:[0,1,0] op_sel_hi:[1,1,1]
	v_pk_fma_f32 v[78:79], v[6:7], v[32:33], v[78:79] op_sel_hi:[1,0,1]
	v_pk_fma_f32 v[92:93], v[6:7], v[28:29], v[92:93] op_sel_hi:[1,0,1]
	v_pk_fma_f32 v[78:79], v[8:9], v[32:33], v[78:79] op_sel:[0,1,0] op_sel_hi:[1,1,1]
	v_pk_mul_f32 v[82:83], v[74:75], v[38:39] op_sel_hi:[1,0]
	v_pk_fma_f32 v[92:93], v[8:9], v[28:29], v[92:93] op_sel:[0,1,0] op_sel_hi:[1,1,1]
	v_pk_mul_f32 v[84:85], v[74:75], v[38:39] op_sel:[0,1] op_sel_hi:[1,1]
	v_add_f32_dpp v78, v78, v78 quad_perm:[1,0,3,2] row_mask:0xf bank_mask:0xf bound_ctrl:1
	v_add_f32_dpp v79, v79, v79 quad_perm:[1,0,3,2] row_mask:0xf bank_mask:0xf bound_ctrl:1
	v_pk_mul_f32 v[86:87], v[74:75], v[40:41] op_sel_hi:[1,0]
	ds_read_b128 v[10:13], v100 offset:30720
	v_add_f32_dpp v78, v78, v78 quad_perm:[2,3,0,1] row_mask:0xf bank_mask:0xf bound_ctrl:1
	v_add_f32_dpp v79, v79, v79 quad_perm:[2,3,0,1] row_mask:0xf bank_mask:0xf bound_ctrl:1
	v_pk_mul_f32 v[88:89], v[74:75], v[40:41] op_sel:[0,1] op_sel_hi:[1,1]
	ds_read_b128 v[18:21], v100 offset:31232
	v_add_f32_dpp v78, v78, v78 row_half_mirror row_mask:0xf bank_mask:0xf bound_ctrl:1
	v_add_f32_dpp v79, v79, v79 row_half_mirror row_mask:0xf bank_mask:0xf bound_ctrl:1
	v_pk_fma_f32 v[82:83], v[2:3], v[34:35], v[82:83] op_sel_hi:[1,0,1]
	ds_read_b128 v[14:17], v100 offset:30976
	v_add_f32_dpp v78, v78, v78 row_mirror row_mask:0xf bank_mask:0xf bound_ctrl:1
	v_add_f32_dpp v79, v79, v79 row_mirror row_mask:0xf bank_mask:0xf bound_ctrl:1
	v_pk_fma_f32 v[84:85], v[4:5], v[34:35], v[84:85] op_sel:[0,1,0] op_sel_hi:[1,1,1]
	ds_read_b128 v[22:25], v100 offset:31488
	v_pk_fma_f32 v[86:87], v[6:7], v[36:37], v[86:87] op_sel_hi:[1,0,1]
	ds_read_b128 v[26:29], v100 offset:31744
	v_pk_fma_f32 v[88:89], v[8:9], v[36:37], v[88:89] op_sel:[0,1,0] op_sel_hi:[1,1,1]
	ds_read_b128 v[70:73], v101 offset:192
	v_cndmask_b32_e64 v116, v112, v114, s[52:53]
	v_cndmask_b32_e64 v118, v114, v112, s[52:53]
	v_cndmask_b32_e64 v117, v113, v115, s[52:53]
	v_pk_fma_f32 v[2:3], v[78:79], v[42:43], v[82:83] op_sel_hi:[1,0,1]
	v_pk_fma_f32 v[4:5], v[78:79], v[42:43], v[84:85] op_sel:[0,1,0] op_sel_hi:[1,1,1]
	v_pk_fma_f32 v[6:7], v[78:79], v[44:45], v[86:87] op_sel_hi:[1,0,1]
	v_pk_fma_f32 v[8:9], v[78:79], v[44:45], v[88:89] op_sel:[0,1,0] op_sel_hi:[1,1,1]
	v_cndmask_b32_e64 v119, v115, v113, s[52:53]
	v_add_f32_dpp v120, v118, v116 quad_perm:[2,3,0,1] row_mask:0xf bank_mask:0xf bound_ctrl:1
	s_nop 0
	v_add_f32_dpp v121, v119, v117 quad_perm:[2,3,0,1] row_mask:0xf bank_mask:0xf bound_ctrl:1
	s_waitcnt lgkmcnt(6)
	v_pk_mul_f32 v[78:79], v[2:3], v[132:133] op_sel_hi:[1,0]
	v_pk_mul_f32 v[94:95], v[2:3], v[46:47] op_sel_hi:[1,0]
	v_pk_fma_f32 v[78:79], v[4:5], v[132:133], v[78:79] op_sel:[0,1,0] op_sel_hi:[1,1,1]
	v_pk_fma_f32 v[94:95], v[4:5], v[46:47], v[94:95] op_sel:[0,1,0] op_sel_hi:[1,1,1]
	v_pk_fma_f32 v[78:79], v[6:7], v[134:135], v[78:79] op_sel_hi:[1,0,1]
	v_pk_fma_f32 v[94:95], v[6:7], v[48:49], v[94:95] op_sel_hi:[1,0,1]
	v_pk_fma_f32 v[78:79], v[8:9], v[134:135], v[78:79] op_sel:[0,1,0] op_sel_hi:[1,1,1]
	v_pk_mul_f32 v[82:83], v[76:77], v[140:141] op_sel_hi:[1,0]
	v_pk_fma_f32 v[94:95], v[8:9], v[48:49], v[94:95] op_sel:[0,1,0] op_sel_hi:[1,1,1]
	v_pk_mul_f32 v[84:85], v[76:77], v[140:141] op_sel:[0,1] op_sel_hi:[1,1]
	v_add_f32_dpp v78, v78, v78 quad_perm:[1,0,3,2] row_mask:0xf bank_mask:0xf bound_ctrl:1
	v_add_f32_dpp v79, v79, v79 quad_perm:[1,0,3,2] row_mask:0xf bank_mask:0xf bound_ctrl:1
	v_pk_mul_f32 v[86:87], v[76:77], v[142:143] op_sel_hi:[1,0]
	ds_read_b128 v[30:33], v100 offset:32000
	v_add_f32_dpp v78, v78, v78 quad_perm:[2,3,0,1] row_mask:0xf bank_mask:0xf bound_ctrl:1
	v_add_f32_dpp v79, v79, v79 quad_perm:[2,3,0,1] row_mask:0xf bank_mask:0xf bound_ctrl:1
	v_pk_mul_f32 v[88:89], v[76:77], v[142:143] op_sel:[0,1] op_sel_hi:[1,1]
	ds_read_b128 v[38:41], v100 offset:32512
	v_add_f32_dpp v78, v78, v78 row_half_mirror row_mask:0xf bank_mask:0xf bound_ctrl:1
	v_add_f32_dpp v79, v79, v79 row_half_mirror row_mask:0xf bank_mask:0xf bound_ctrl:1
	v_pk_fma_f32 v[82:83], v[2:3], v[136:137], v[82:83] op_sel_hi:[1,0,1]
	ds_read_b128 v[34:37], v100 offset:32256
	v_add_f32_dpp v78, v78, v78 row_mirror row_mask:0xf bank_mask:0xf bound_ctrl:1
	v_add_f32_dpp v79, v79, v79 row_mirror row_mask:0xf bank_mask:0xf bound_ctrl:1
	v_pk_fma_f32 v[84:85], v[4:5], v[136:137], v[84:85] op_sel:[0,1,0] op_sel_hi:[1,1,1]
	ds_read_b128 v[42:45], v100 offset:32768
	v_pk_fma_f32 v[86:87], v[6:7], v[138:139], v[86:87] op_sel_hi:[1,0,1]
	ds_read_b128 v[46:49], v100 offset:33024
	v_pk_fma_f32 v[88:89], v[8:9], v[138:139], v[88:89] op_sel:[0,1,0] op_sel_hi:[1,1,1]
	v_add_f32_dpp v120, v120, v120 row_ror:4 row_mask:0xf bank_mask:0xf bound_ctrl:1
	v_add_f32_dpp v121, v121, v121 row_ror:4 row_mask:0xf bank_mask:0xf bound_ctrl:1
	s_nop 0
	v_add_f32_dpp v120, v120, v120 row_ror:8 row_mask:0xf bank_mask:0xf bound_ctrl:1
	v_pk_fma_f32 v[2:3], v[78:79], v[144:145], v[82:83] op_sel_hi:[1,0,1]
	v_pk_fma_f32 v[4:5], v[78:79], v[144:145], v[84:85] op_sel:[0,1,0] op_sel_hi:[1,1,1]
	v_pk_fma_f32 v[6:7], v[78:79], v[146:147], v[86:87] op_sel_hi:[1,0,1]
	v_pk_fma_f32 v[8:9], v[78:79], v[146:147], v[88:89] op_sel:[0,1,0] op_sel_hi:[1,1,1]
	v_add_f32_dpp v121, v121, v121 row_ror:8 row_mask:0xf bank_mask:0xf bound_ctrl:1
	global_store_dwordx2 v102, v[120:121], s[10:11]
	v_add_u32_e32 v102, s13, v102
	s_waitcnt lgkmcnt(5)
; #define LAS __attribute__((address_space(3)))
; __device__ __forceinline__ void phase_scan(CParams& P, LAS unsigned char* lds) {
;     ...
; #pragma unroll 2
;                 for (int j = 0; j < CH; j += 2) { const LAS float* sp = base + j * STEPF;
;                     SC_LOAD(B, sp + STEPF); SC_STEP(A);
;                     SC_LOAD(A, sp + 2 * STEPF);
;                     SC_STEP(B); }
	v_pk_mul_f32 v[78:79], v[2:3], v[10:11] op_sel_hi:[1,0]
	v_pk_mul_f32 v[96:97], v[2:3], v[148:149] op_sel_hi:[1,0]
	v_pk_fma_f32 v[78:79], v[4:5], v[10:11], v[78:79] op_sel:[0,1,0] op_sel_hi:[1,1,1]
	v_pk_fma_f32 v[96:97], v[4:5], v[148:149], v[96:97] op_sel:[0,1,0] op_sel_hi:[1,1,1]
	v_pk_fma_f32 v[78:79], v[6:7], v[12:13], v[78:79] op_sel_hi:[1,0,1]
	v_pk_fma_f32 v[96:97], v[6:7], v[150:151], v[96:97] op_sel_hi:[1,0,1]
	v_pk_fma_f32 v[78:79], v[8:9], v[12:13], v[78:79] op_sel:[0,1,0] op_sel_hi:[1,1,1]
	v_pk_mul_f32 v[82:83], v[70:71], v[18:19] op_sel_hi:[1,0]
	v_pk_fma_f32 v[96:97], v[8:9], v[150:151], v[96:97] op_sel:[0,1,0] op_sel_hi:[1,1,1]
	v_pk_mul_f32 v[84:85], v[70:71], v[18:19] op_sel:[0,1] op_sel_hi:[1,1]
	v_add_f32_dpp v78, v78, v78 quad_perm:[1,0,3,2] row_mask:0xf bank_mask:0xf bound_ctrl:1
	v_add_f32_dpp v79, v79, v79 quad_perm:[1,0,3,2] row_mask:0xf bank_mask:0xf bound_ctrl:1
	v_pk_mul_f32 v[86:87], v[70:71], v[20:21] op_sel_hi:[1,0]
	ds_read_b128 v[132:135], v100 offset:33280
	v_add_f32_dpp v78, v78, v78 quad_perm:[2,3,0,1] row_mask:0xf bank_mask:0xf bound_ctrl:1
	v_add_f32_dpp v79, v79, v79 quad_perm:[2,3,0,1] row_mask:0xf bank_mask:0xf bound_ctrl:1
	v_pk_mul_f32 v[88:89], v[70:71], v[20:21] op_sel:[0,1] op_sel_hi:[1,1]
	ds_read_b128 v[140:143], v100 offset:33792
	v_add_f32_dpp v78, v78, v78 row_half_mirror row_mask:0xf bank_mask:0xf bound_ctrl:1
	v_add_f32_dpp v79, v79, v79 row_half_mirror row_mask:0xf bank_mask:0xf bound_ctrl:1
	v_pk_fma_f32 v[82:83], v[2:3], v[14:15], v[82:83] op_sel_hi:[1,0,1]
	ds_read_b128 v[136:139], v100 offset:33536
	v_add_f32_dpp v78, v78, v78 row_mirror row_mask:0xf bank_mask:0xf bound_ctrl:1
	v_add_f32_dpp v79, v79, v79 row_mirror row_mask:0xf bank_mask:0xf bound_ctrl:1
	v_pk_fma_f32 v[84:85], v[4:5], v[14:15], v[84:85] op_sel:[0,1,0] op_sel_hi:[1,1,1]
	ds_read_b128 v[144:147], v100 offset:34048
	v_pk_fma_f32 v[86:87], v[6:7], v[16:17], v[86:87] op_sel_hi:[1,0,1]
	ds_read_b128 v[148:151], v100 offset:34304
	v_pk_fma_f32 v[88:89], v[8:9], v[16:17], v[88:89] op_sel:[0,1,0] op_sel_hi:[1,1,1]
	ds_read_b128 v[74:77], v101 offset:208
	v_cndmask_b32_e64 v104, v90, v92, s[50:51]
	v_cndmask_b32_e64 v106, v92, v90, s[50:51]
	v_cndmask_b32_e64 v108, v94, v96, s[50:51]
	v_pk_fma_f32 v[2:3], v[78:79], v[22:23], v[82:83] op_sel_hi:[1,0,1]
	v_pk_fma_f32 v[4:5], v[78:79], v[22:23], v[84:85] op_sel:[0,1,0] op_sel_hi:[1,1,1]
	v_pk_fma_f32 v[6:7], v[78:79], v[24:25], v[86:87] op_sel_hi:[1,0,1]
	v_pk_fma_f32 v[8:9], v[78:79], v[24:25], v[88:89] op_sel:[0,1,0] op_sel_hi:[1,1,1]
	v_cndmask_b32_e64 v110, v96, v94, s[50:51]
	v_cndmask_b32_e64 v105, v91, v93, s[50:51]
	v_cndmask_b32_e64 v107, v93, v91, s[50:51]
	s_waitcnt lgkmcnt(6)
	v_pk_mul_f32 v[78:79], v[2:3], v[30:31] op_sel_hi:[1,0]
	v_pk_mul_f32 v[90:91], v[2:3], v[26:27] op_sel_hi:[1,0]
	v_pk_fma_f32 v[78:79], v[4:5], v[30:31], v[78:79] op_sel:[0,1,0] op_sel_hi:[1,1,1]
	v_pk_fma_f32 v[90:91], v[4:5], v[26:27], v[90:91] op_sel:[0,1,0] op_sel_hi:[1,1,1]
	v_pk_fma_f32 v[78:79], v[6:7], v[32:33], v[78:79] op_sel_hi:[1,0,1]
	v_pk_fma_f32 v[90:91], v[6:7], v[28:29], v[90:91] op_sel_hi:[1,0,1]
	v_pk_fma_f32 v[78:79], v[8:9], v[32:33], v[78:79] op_sel:[0,1,0] op_sel_hi:[1,1,1]
	v_pk_mul_f32 v[82:83], v[72:73], v[38:39] op_sel_hi:[1,0]
	v_pk_fma_f32 v[90:91], v[8:9], v[28:29], v[90:91] op_sel:[0,1,0] op_sel_hi:[1,1,1]
	v_pk_mul_f32 v[84:85], v[72:73], v[38:39] op_sel:[0,1] op_sel_hi:[1,1]
	v_add_f32_dpp v78, v78, v78 quad_perm:[1,0,3,2] row_mask:0xf bank_mask:0xf bound_ctrl:1
	v_add_f32_dpp v79, v79, v79 quad_perm:[1,0,3,2] row_mask:0xf bank_mask:0xf bound_ctrl:1
	v_pk_mul_f32 v[86:87], v[72:73], v[40:41] op_sel_hi:[1,0]
	ds_read_b128 v[10:13], v100 offset:34560
	v_add_f32_dpp v78, v78, v78 quad_perm:[2,3,0,1] row_mask:0xf bank_mask:0xf bound_ctrl:1
	v_add_f32_dpp v79, v79, v79 quad_perm:[2,3,0,1] row_mask:0xf bank_mask:0xf bound_ctrl:1
	v_pk_mul_f32 v[88:89], v[72:73], v[40:41] op_sel:[0,1] op_sel_hi:[1,1]
	ds_read_b128 v[18:21], v100 offset:35072
	v_add_f32_dpp v78, v78, v78 row_half_mirror row_mask:0xf bank_mask:0xf bound_ctrl:1
	v_add_f32_dpp v79, v79, v79 row_half_mirror row_mask:0xf bank_mask:0xf bound_ctrl:1
	v_pk_fma_f32 v[82:83], v[2:3], v[34:35], v[82:83] op_sel_hi:[1,0,1]
	ds_read_b128 v[14:17], v100 offset:34816
	v_add_f32_dpp v78, v78, v78 row_mirror row_mask:0xf bank_mask:0xf bound_ctrl:1
	v_add_f32_dpp v79, v79, v79 row_mirror row_mask:0xf bank_mask:0xf bound_ctrl:1
	v_pk_fma_f32 v[84:85], v[4:5], v[34:35], v[84:85] op_sel:[0,1,0] op_sel_hi:[1,1,1]
	ds_read_b128 v[22:25], v100 offset:35328
	v_pk_fma_f32 v[86:87], v[6:7], v[36:37], v[86:87] op_sel_hi:[1,0,1]
	ds_read_b128 v[26:29], v100 offset:35584
	v_pk_fma_f32 v[88:89], v[8:9], v[36:37], v[88:89] op_sel:[0,1,0] op_sel_hi:[1,1,1]
	v_cndmask_b32_e64 v109, v95, v97, s[50:51]
	v_cndmask_b32_e64 v111, v97, v95, s[50:51]
	v_add_f32_dpp v112, v106, v104 quad_perm:[1,0,3,2] row_mask:0xf bank_mask:0xf bound_ctrl:1
	v_pk_fma_f32 v[2:3], v[78:79], v[42:43], v[82:83] op_sel_hi:[1,0,1]
	v_pk_fma_f32 v[4:5], v[78:79], v[42:43], v[84:85] op_sel:[0,1,0] op_sel_hi:[1,1,1]
	v_pk_fma_f32 v[6:7], v[78:79], v[44:45], v[86:87] op_sel_hi:[1,0,1]
	v_pk_fma_f32 v[8:9], v[78:79], v[44:45], v[88:89] op_sel:[0,1,0] op_sel_hi:[1,1,1]
	v_add_f32_dpp v114, v110, v108 quad_perm:[1,0,3,2] row_mask:0xf bank_mask:0xf bound_ctrl:1
	v_add_f32_dpp v113, v107, v105 quad_perm:[1,0,3,2] row_mask:0xf bank_mask:0xf bound_ctrl:1
	v_add_f32_dpp v115, v111, v109 quad_perm:[1,0,3,2] row_mask:0xf bank_mask:0xf bound_ctrl:1
	s_waitcnt lgkmcnt(5)
; #define LAS __attribute__((address_space(3)))
; __device__ __forceinline__ void phase_scan(CParams& P, LAS unsigned char* lds) {
;     ...
; #pragma unroll 2
;                 for (int j = 0; j < CH; j += 2) { const LAS float* sp = base + j * STEPF;
;                     SC_LOAD(B, sp + STEPF); SC_STEP(A);
;                     SC_LOAD(A, sp + 2 * STEPF);
;                     SC_STEP(B); }
	v_pk_mul_f32 v[78:79], v[2:3], v[132:133] op_sel_hi:[1,0]
	v_pk_mul_f32 v[92:93], v[2:3], v[46:47] op_sel_hi:[1,0]
	v_pk_fma_f32 v[78:79], v[4:5], v[132:133], v[78:79] op_sel:[0,1,0] op_sel_hi:[1,1,1]
	v_pk_fma_f32 v[92:93], v[4:5], v[46:47], v[92:93] op_sel:[0,1,0] op_sel_hi:[1,1,1]
	v_pk_fma_f32 v[78:79], v[6:7], v[134:135], v[78:79] op_sel_hi:[1,0,1]
	v_pk_fma_f32 v[92:93], v[6:7], v[48:49], v[92:93] op_sel_hi:[1,0,1]
	v_pk_fma_f32 v[78:79], v[8:9], v[134:135], v[78:79] op_sel:[0,1,0] op_sel_hi:[1,1,1]
	v_pk_mul_f32 v[82:83], v[74:75], v[140:141] op_sel_hi:[1,0]
	v_pk_fma_f32 v[92:93], v[8:9], v[48:49], v[92:93] op_sel:[0,1,0] op_sel_hi:[1,1,1]
	v_pk_mul_f32 v[84:85], v[74:75], v[140:141] op_sel:[0,1] op_sel_hi:[1,1]
	v_add_f32_dpp v78, v78, v78 quad_perm:[1,0,3,2] row_mask:0xf bank_mask:0xf bound_ctrl:1
	v_add_f32_dpp v79, v79, v79 quad_perm:[1,0,3,2] row_mask:0xf bank_mask:0xf bound_ctrl:1
	v_pk_mul_f32 v[86:87], v[74:75], v[142:143] op_sel_hi:[1,0]
	ds_read_b128 v[30:33], v100 offset:35840
	v_add_f32_dpp v78, v78, v78 quad_perm:[2,3,0,1] row_mask:0xf bank_mask:0xf bound_ctrl:1
	v_add_f32_dpp v79, v79, v79 quad_perm:[2,3,0,1] row_mask:0xf bank_mask:0xf bound_ctrl:1
	v_pk_mul_f32 v[88:89], v[74:75], v[142:143] op_sel:[0,1] op_sel_hi:[1,1]
	ds_read_b128 v[38:41], v100 offset:36352
	v_add_f32_dpp v78, v78, v78 row_half_mirror row_mask:0xf bank_mask:0xf bound_ctrl:1
	v_add_f32_dpp v79, v79, v79 row_half_mirror row_mask:0xf bank_mask:0xf bound_ctrl:1
	v_pk_fma_f32 v[82:83], v[2:3], v[136:137], v[82:83] op_sel_hi:[1,0,1]
	ds_read_b128 v[34:37], v100 offset:36096
	v_add_f32_dpp v78, v78, v78 row_mirror row_mask:0xf bank_mask:0xf bound_ctrl:1
	v_add_f32_dpp v79, v79, v79 row_mirror row_mask:0xf bank_mask:0xf bound_ctrl:1
	v_pk_fma_f32 v[84:85], v[4:5], v[136:137], v[84:85] op_sel:[0,1,0] op_sel_hi:[1,1,1]
	ds_read_b128 v[42:45], v100 offset:36608
	v_pk_fma_f32 v[86:87], v[6:7], v[138:139], v[86:87] op_sel_hi:[1,0,1]
	ds_read_b128 v[46:49], v100 offset:36864
	v_pk_fma_f32 v[88:89], v[8:9], v[138:139], v[88:89] op_sel:[0,1,0] op_sel_hi:[1,1,1]
	ds_read_b128 v[70:73], v101 offset:224
	v_cndmask_b32_e64 v116, v112, v114, s[52:53]
	v_cndmask_b32_e64 v118, v114, v112, s[52:53]
	v_cndmask_b32_e64 v117, v113, v115, s[52:53]
	v_pk_fma_f32 v[2:3], v[78:79], v[144:145], v[82:83] op_sel_hi:[1,0,1]
	v_pk_fma_f32 v[4:5], v[78:79], v[144:145], v[84:85] op_sel:[0,1,0] op_sel_hi:[1,1,1]
	v_pk_fma_f32 v[6:7], v[78:79], v[146:147], v[86:87] op_sel_hi:[1,0,1]
	v_pk_fma_f32 v[8:9], v[78:79], v[146:147], v[88:89] op_sel:[0,1,0] op_sel_hi:[1,1,1]
	v_cndmask_b32_e64 v119, v115, v113, s[52:53]
	v_add_f32_dpp v120, v118, v116 quad_perm:[2,3,0,1] row_mask:0xf bank_mask:0xf bound_ctrl:1
	s_nop 0
	v_add_f32_dpp v121, v119, v117 quad_perm:[2,3,0,1] row_mask:0xf bank_mask:0xf bound_ctrl:1
	s_waitcnt lgkmcnt(6)
	v_pk_mul_f32 v[78:79], v[2:3], v[10:11] op_sel_hi:[1,0]
	v_pk_mul_f32 v[94:95], v[2:3], v[148:149] op_sel_hi:[1,0]
	v_pk_fma_f32 v[78:79], v[4:5], v[10:11], v[78:79] op_sel:[0,1,0] op_sel_hi:[1,1,1]
	v_pk_fma_f32 v[94:95], v[4:5], v[148:149], v[94:95] op_sel:[0,1,0] op_sel_hi:[1,1,1]
	v_pk_fma_f32 v[78:79], v[6:7], v[12:13], v[78:79] op_sel_hi:[1,0,1]
	v_pk_fma_f32 v[94:95], v[6:7], v[150:151], v[94:95] op_sel_hi:[1,0,1]
	v_pk_fma_f32 v[78:79], v[8:9], v[12:13], v[78:79] op_sel:[0,1,0] op_sel_hi:[1,1,1]
	v_pk_mul_f32 v[82:83], v[76:77], v[18:19] op_sel_hi:[1,0]
	v_pk_fma_f32 v[94:95], v[8:9], v[150:151], v[94:95] op_sel:[0,1,0] op_sel_hi:[1,1,1]
	v_pk_mul_f32 v[84:85], v[76:77], v[18:19] op_sel:[0,1] op_sel_hi:[1,1]
	v_add_f32_dpp v78, v78, v78 quad_perm:[1,0,3,2] row_mask:0xf bank_mask:0xf bound_ctrl:1
	v_add_f32_dpp v79, v79, v79 quad_perm:[1,0,3,2] row_mask:0xf bank_mask:0xf bound_ctrl:1
	v_pk_mul_f32 v[86:87], v[76:77], v[20:21] op_sel_hi:[1,0]
	ds_read_b128 v[132:135], v100 offset:37120
	v_add_f32_dpp v78, v78, v78 quad_perm:[2,3,0,1] row_mask:0xf bank_mask:0xf bound_ctrl:1
	v_add_f32_dpp v79, v79, v79 quad_perm:[2,3,0,1] row_mask:0xf bank_mask:0xf bound_ctrl:1
	v_pk_mul_f32 v[88:89], v[76:77], v[20:21] op_sel:[0,1] op_sel_hi:[1,1]
	ds_read_b128 v[140:143], v100 offset:37632
	v_add_f32_dpp v78, v78, v78 row_half_mirror row_mask:0xf bank_mask:0xf bound_ctrl:1
	v_add_f32_dpp v79, v79, v79 row_half_mirror row_mask:0xf bank_mask:0xf bound_ctrl:1
	v_pk_fma_f32 v[82:83], v[2:3], v[14:15], v[82:83] op_sel_hi:[1,0,1]
	ds_read_b128 v[136:139], v100 offset:37376
	v_add_f32_dpp v78, v78, v78 row_mirror row_mask:0xf bank_mask:0xf bound_ctrl:1
	v_add_f32_dpp v79, v79, v79 row_mirror row_mask:0xf bank_mask:0xf bound_ctrl:1
	v_pk_fma_f32 v[84:85], v[4:5], v[14:15], v[84:85] op_sel:[0,1,0] op_sel_hi:[1,1,1]
	ds_read_b128 v[144:147], v100 offset:37888
	v_pk_fma_f32 v[86:87], v[6:7], v[16:17], v[86:87] op_sel_hi:[1,0,1]
	ds_read_b128 v[148:151], v100 offset:38144
	v_pk_fma_f32 v[88:89], v[8:9], v[16:17], v[88:89] op_sel:[0,1,0] op_sel_hi:[1,1,1]
	v_add_f32_dpp v120, v120, v120 row_ror:4 row_mask:0xf bank_mask:0xf bound_ctrl:1
	v_add_f32_dpp v121, v121, v121 row_ror:4 row_mask:0xf bank_mask:0xf bound_ctrl:1
	s_nop 0
	v_add_f32_dpp v120, v120, v120 row_ror:8 row_mask:0xf bank_mask:0xf bound_ctrl:1
	v_pk_fma_f32 v[2:3], v[78:79], v[22:23], v[82:83] op_sel_hi:[1,0,1]
	v_pk_fma_f32 v[4:5], v[78:79], v[22:23], v[84:85] op_sel:[0,1,0] op_sel_hi:[1,1,1]
	v_pk_fma_f32 v[6:7], v[78:79], v[24:25], v[86:87] op_sel_hi:[1,0,1]
	v_pk_fma_f32 v[8:9], v[78:79], v[24:25], v[88:89] op_sel:[0,1,0] op_sel_hi:[1,1,1]
	v_add_f32_dpp v121, v121, v121 row_ror:8 row_mask:0xf bank_mask:0xf bound_ctrl:1
	global_store_dwordx2 v102, v[120:121], s[10:11]
	v_add_u32_e32 v102, s13, v102
	s_waitcnt lgkmcnt(5)
; #define LAS __attribute__((address_space(3)))
; __device__ __forceinline__ void phase_scan(CParams& P, LAS unsigned char* lds) {
;     ...
;             f32x4 Ar0, Ar1, Aw0, Aw1, Ak0, Ak1, Aq0, Aq1, Ab0, Ab1, Br0, Br1, Bw0, Bw1, Bk0, Bk1, Bq0, Bq1, Bb0, Bb1; float Avv, Bvv;
; #pragma unroll 1
;             for (int c = 0; c < NCH; ++c) {
;                 __syncthreads();
;                 const LAS float* base = lf + (c & 1) * BUFF + 8 * oct;
;                 SC_LOAD(A, base);
; #pragma unroll 2
;                 for (int j = 0; j < CH; j += 2) { const LAS float* sp = base + j * STEPF;
;                     SC_LOAD(B, sp + STEPF); SC_STEP(A);
;                     SC_LOAD(A, sp + 2 * STEPF);
;                     SC_STEP(B); }
;             }
	v_pk_mul_f32 v[78:79], v[2:3], v[30:31] op_sel_hi:[1,0]
	v_pk_mul_f32 v[96:97], v[2:3], v[26:27] op_sel_hi:[1,0]
	v_pk_fma_f32 v[78:79], v[4:5], v[30:31], v[78:79] op_sel:[0,1,0] op_sel_hi:[1,1,1]
	v_pk_fma_f32 v[96:97], v[4:5], v[26:27], v[96:97] op_sel:[0,1,0] op_sel_hi:[1,1,1]
	v_pk_fma_f32 v[78:79], v[6:7], v[32:33], v[78:79] op_sel_hi:[1,0,1]
	v_pk_fma_f32 v[96:97], v[6:7], v[28:29], v[96:97] op_sel_hi:[1,0,1]
	v_pk_fma_f32 v[78:79], v[8:9], v[32:33], v[78:79] op_sel:[0,1,0] op_sel_hi:[1,1,1]
	v_pk_mul_f32 v[82:83], v[70:71], v[38:39] op_sel_hi:[1,0]
	v_pk_fma_f32 v[96:97], v[8:9], v[28:29], v[96:97] op_sel:[0,1,0] op_sel_hi:[1,1,1]
	v_pk_mul_f32 v[84:85], v[70:71], v[38:39] op_sel:[0,1] op_sel_hi:[1,1]
	v_add_f32_dpp v78, v78, v78 quad_perm:[1,0,3,2] row_mask:0xf bank_mask:0xf bound_ctrl:1
	v_add_f32_dpp v79, v79, v79 quad_perm:[1,0,3,2] row_mask:0xf bank_mask:0xf bound_ctrl:1
	v_pk_mul_f32 v[86:87], v[70:71], v[40:41] op_sel_hi:[1,0]
	ds_read_b128 v[10:13], v100 offset:38400
	v_add_f32_dpp v78, v78, v78 quad_perm:[2,3,0,1] row_mask:0xf bank_mask:0xf bound_ctrl:1
	v_add_f32_dpp v79, v79, v79 quad_perm:[2,3,0,1] row_mask:0xf bank_mask:0xf bound_ctrl:1
	v_pk_mul_f32 v[88:89], v[70:71], v[40:41] op_sel:[0,1] op_sel_hi:[1,1]
	ds_read_b128 v[18:21], v100 offset:38912
	v_add_f32_dpp v78, v78, v78 row_half_mirror row_mask:0xf bank_mask:0xf bound_ctrl:1
	v_add_f32_dpp v79, v79, v79 row_half_mirror row_mask:0xf bank_mask:0xf bound_ctrl:1
	v_pk_fma_f32 v[82:83], v[2:3], v[34:35], v[82:83] op_sel_hi:[1,0,1]
	ds_read_b128 v[14:17], v100 offset:38656
	v_add_f32_dpp v78, v78, v78 row_mirror row_mask:0xf bank_mask:0xf bound_ctrl:1
	v_add_f32_dpp v79, v79, v79 row_mirror row_mask:0xf bank_mask:0xf bound_ctrl:1
	v_pk_fma_f32 v[84:85], v[4:5], v[34:35], v[84:85] op_sel:[0,1,0] op_sel_hi:[1,1,1]
	ds_read_b128 v[22:25], v100 offset:39168
	v_pk_fma_f32 v[86:87], v[6:7], v[36:37], v[86:87] op_sel_hi:[1,0,1]
	ds_read_b128 v[26:29], v100 offset:39424
	v_pk_fma_f32 v[88:89], v[8:9], v[36:37], v[88:89] op_sel:[0,1,0] op_sel_hi:[1,1,1]
	ds_read_b128 v[74:77], v101 offset:240
	v_cndmask_b32_e64 v104, v90, v92, s[50:51]
	v_cndmask_b32_e64 v106, v92, v90, s[50:51]
	v_cndmask_b32_e64 v108, v94, v96, s[50:51]
	v_pk_fma_f32 v[2:3], v[78:79], v[42:43], v[82:83] op_sel_hi:[1,0,1]
	v_pk_fma_f32 v[4:5], v[78:79], v[42:43], v[84:85] op_sel:[0,1,0] op_sel_hi:[1,1,1]
	v_pk_fma_f32 v[6:7], v[78:79], v[44:45], v[86:87] op_sel_hi:[1,0,1]
	v_pk_fma_f32 v[8:9], v[78:79], v[44:45], v[88:89] op_sel:[0,1,0] op_sel_hi:[1,1,1]
	v_cndmask_b32_e64 v110, v96, v94, s[50:51]
	v_cndmask_b32_e64 v105, v91, v93, s[50:51]
	v_cndmask_b32_e64 v107, v93, v91, s[50:51]
	s_waitcnt lgkmcnt(6)
	v_pk_mul_f32 v[78:79], v[2:3], v[132:133] op_sel_hi:[1,0]
	v_pk_mul_f32 v[90:91], v[2:3], v[46:47] op_sel_hi:[1,0]
	v_pk_fma_f32 v[78:79], v[4:5], v[132:133], v[78:79] op_sel:[0,1,0] op_sel_hi:[1,1,1]
	v_pk_fma_f32 v[90:91], v[4:5], v[46:47], v[90:91] op_sel:[0,1,0] op_sel_hi:[1,1,1]
	v_pk_fma_f32 v[78:79], v[6:7], v[134:135], v[78:79] op_sel_hi:[1,0,1]
	v_pk_fma_f32 v[90:91], v[6:7], v[48:49], v[90:91] op_sel_hi:[1,0,1]
	v_pk_fma_f32 v[78:79], v[8:9], v[134:135], v[78:79] op_sel:[0,1,0] op_sel_hi:[1,1,1]
	v_pk_mul_f32 v[82:83], v[72:73], v[140:141] op_sel_hi:[1,0]
	v_pk_fma_f32 v[90:91], v[8:9], v[48:49], v[90:91] op_sel:[0,1,0] op_sel_hi:[1,1,1]
	v_pk_mul_f32 v[84:85], v[72:73], v[140:141] op_sel:[0,1] op_sel_hi:[1,1]
	v_add_f32_dpp v78, v78, v78 quad_perm:[1,0,3,2] row_mask:0xf bank_mask:0xf bound_ctrl:1
	v_add_f32_dpp v79, v79, v79 quad_perm:[1,0,3,2] row_mask:0xf bank_mask:0xf bound_ctrl:1
	v_pk_mul_f32 v[86:87], v[72:73], v[142:143] op_sel_hi:[1,0]
	ds_read_b128 v[30:33], v100 offset:39680
	v_add_f32_dpp v78, v78, v78 quad_perm:[2,3,0,1] row_mask:0xf bank_mask:0xf bound_ctrl:1
	v_add_f32_dpp v79, v79, v79 quad_perm:[2,3,0,1] row_mask:0xf bank_mask:0xf bound_ctrl:1
	v_pk_mul_f32 v[88:89], v[72:73], v[142:143] op_sel:[0,1] op_sel_hi:[1,1]
	ds_read_b128 v[38:41], v100 offset:40192
	v_add_f32_dpp v78, v78, v78 row_half_mirror row_mask:0xf bank_mask:0xf bound_ctrl:1
	v_add_f32_dpp v79, v79, v79 row_half_mirror row_mask:0xf bank_mask:0xf bound_ctrl:1
	v_pk_fma_f32 v[82:83], v[2:3], v[136:137], v[82:83] op_sel_hi:[1,0,1]
	ds_read_b128 v[34:37], v100 offset:39936
	v_add_f32_dpp v78, v78, v78 row_mirror row_mask:0xf bank_mask:0xf bound_ctrl:1
	v_add_f32_dpp v79, v79, v79 row_mirror row_mask:0xf bank_mask:0xf bound_ctrl:1
	v_pk_fma_f32 v[84:85], v[4:5], v[136:137], v[84:85] op_sel:[0,1,0] op_sel_hi:[1,1,1]
	ds_read_b128 v[42:45], v100 offset:40448
	v_pk_fma_f32 v[86:87], v[6:7], v[138:139], v[86:87] op_sel_hi:[1,0,1]
	ds_read_b128 v[46:49], v100 offset:40704
	v_pk_fma_f32 v[88:89], v[8:9], v[138:139], v[88:89] op_sel:[0,1,0] op_sel_hi:[1,1,1]
	v_cndmask_b32_e64 v109, v95, v97, s[50:51]
	v_cndmask_b32_e64 v111, v97, v95, s[50:51]
	v_add_f32_dpp v112, v106, v104 quad_perm:[1,0,3,2] row_mask:0xf bank_mask:0xf bound_ctrl:1
	v_pk_fma_f32 v[2:3], v[78:79], v[144:145], v[82:83] op_sel_hi:[1,0,1]
	v_pk_fma_f32 v[4:5], v[78:79], v[144:145], v[84:85] op_sel:[0,1,0] op_sel_hi:[1,1,1]
	v_pk_fma_f32 v[6:7], v[78:79], v[146:147], v[86:87] op_sel_hi:[1,0,1]
	v_pk_fma_f32 v[8:9], v[78:79], v[146:147], v[88:89] op_sel:[0,1,0] op_sel_hi:[1,1,1]
	v_add_f32_dpp v114, v110, v108 quad_perm:[1,0,3,2] row_mask:0xf bank_mask:0xf bound_ctrl:1
	v_add_f32_dpp v113, v107, v105 quad_perm:[1,0,3,2] row_mask:0xf bank_mask:0xf bound_ctrl:1
	v_add_f32_dpp v115, v111, v109 quad_perm:[1,0,3,2] row_mask:0xf bank_mask:0xf bound_ctrl:1
	s_waitcnt lgkmcnt(5)
; #define LAS __attribute__((address_space(3)))
; __device__ __forceinline__ void phase_scan(CParams& P, LAS unsigned char* lds) {
;     ...
;             f32x4 Ar0, Ar1, Aw0, Aw1, Ak0, Ak1, Aq0, Aq1, Ab0, Ab1, Br0, Br1, Bw0, Bw1, Bk0, Bk1, Bq0, Bq1, Bb0, Bb1; float Avv, Bvv;
; #pragma unroll 1
;             for (int c = 0; c < NCH; ++c) {
;                 __syncthreads();
;                 const LAS float* base = lf + (c & 1) * BUFF + 8 * oct;
;                 SC_LOAD(A, base);
; #pragma unroll 2
;                 for (int j = 0; j < CH; j += 2) { const LAS float* sp = base + j * STEPF;
;                     SC_LOAD(B, sp + STEPF); SC_STEP(A);
;                     SC_LOAD(A, sp + 2 * STEPF);
;                     SC_STEP(B); }
;             }
	v_pk_mul_f32 v[78:79], v[2:3], v[10:11] op_sel_hi:[1,0]
	v_pk_mul_f32 v[92:93], v[2:3], v[148:149] op_sel_hi:[1,0]
	v_pk_fma_f32 v[78:79], v[4:5], v[10:11], v[78:79] op_sel:[0,1,0] op_sel_hi:[1,1,1]
	v_pk_fma_f32 v[92:93], v[4:5], v[148:149], v[92:93] op_sel:[0,1,0] op_sel_hi:[1,1,1]
	v_pk_fma_f32 v[78:79], v[6:7], v[12:13], v[78:79] op_sel_hi:[1,0,1]
	v_pk_fma_f32 v[92:93], v[6:7], v[150:151], v[92:93] op_sel_hi:[1,0,1]
	v_pk_fma_f32 v[78:79], v[8:9], v[12:13], v[78:79] op_sel:[0,1,0] op_sel_hi:[1,1,1]
	v_pk_mul_f32 v[82:83], v[74:75], v[18:19] op_sel_hi:[1,0]
	v_pk_fma_f32 v[92:93], v[8:9], v[150:151], v[92:93] op_sel:[0,1,0] op_sel_hi:[1,1,1]
	v_pk_mul_f32 v[84:85], v[74:75], v[18:19] op_sel:[0,1] op_sel_hi:[1,1]
	v_add_f32_dpp v78, v78, v78 quad_perm:[1,0,3,2] row_mask:0xf bank_mask:0xf bound_ctrl:1
	v_add_f32_dpp v79, v79, v79 quad_perm:[1,0,3,2] row_mask:0xf bank_mask:0xf bound_ctrl:1
	v_pk_mul_f32 v[86:87], v[74:75], v[20:21] op_sel_hi:[1,0]
	v_add_f32_dpp v78, v78, v78 quad_perm:[2,3,0,1] row_mask:0xf bank_mask:0xf bound_ctrl:1
	v_add_f32_dpp v79, v79, v79 quad_perm:[2,3,0,1] row_mask:0xf bank_mask:0xf bound_ctrl:1
	v_pk_mul_f32 v[88:89], v[74:75], v[20:21] op_sel:[0,1] op_sel_hi:[1,1]
	v_add_f32_dpp v78, v78, v78 row_half_mirror row_mask:0xf bank_mask:0xf bound_ctrl:1
	v_add_f32_dpp v79, v79, v79 row_half_mirror row_mask:0xf bank_mask:0xf bound_ctrl:1
	v_pk_fma_f32 v[82:83], v[2:3], v[14:15], v[82:83] op_sel_hi:[1,0,1]
	v_add_f32_dpp v78, v78, v78 row_mirror row_mask:0xf bank_mask:0xf bound_ctrl:1
	v_add_f32_dpp v79, v79, v79 row_mirror row_mask:0xf bank_mask:0xf bound_ctrl:1
	v_pk_fma_f32 v[84:85], v[4:5], v[14:15], v[84:85] op_sel:[0,1,0] op_sel_hi:[1,1,1]
	v_pk_fma_f32 v[86:87], v[6:7], v[16:17], v[86:87] op_sel_hi:[1,0,1]
	v_pk_fma_f32 v[88:89], v[8:9], v[16:17], v[88:89] op_sel:[0,1,0] op_sel_hi:[1,1,1]
	v_cndmask_b32_e64 v116, v112, v114, s[52:53]
	v_cndmask_b32_e64 v118, v114, v112, s[52:53]
	v_cndmask_b32_e64 v117, v113, v115, s[52:53]
	v_pk_fma_f32 v[2:3], v[78:79], v[22:23], v[82:83] op_sel_hi:[1,0,1]
	v_pk_fma_f32 v[4:5], v[78:79], v[22:23], v[84:85] op_sel:[0,1,0] op_sel_hi:[1,1,1]
	v_pk_fma_f32 v[6:7], v[78:79], v[24:25], v[86:87] op_sel_hi:[1,0,1]
	v_pk_fma_f32 v[8:9], v[78:79], v[24:25], v[88:89] op_sel:[0,1,0] op_sel_hi:[1,1,1]
	v_cndmask_b32_e64 v119, v115, v113, s[52:53]
	v_add_f32_dpp v120, v118, v116 quad_perm:[2,3,0,1] row_mask:0xf bank_mask:0xf bound_ctrl:1
	s_nop 0
	v_add_f32_dpp v121, v119, v117 quad_perm:[2,3,0,1] row_mask:0xf bank_mask:0xf bound_ctrl:1
	s_waitcnt lgkmcnt(0)
	v_pk_mul_f32 v[78:79], v[2:3], v[30:31] op_sel_hi:[1,0]
	v_pk_mul_f32 v[94:95], v[2:3], v[26:27] op_sel_hi:[1,0]
	v_pk_fma_f32 v[78:79], v[4:5], v[30:31], v[78:79] op_sel:[0,1,0] op_sel_hi:[1,1,1]
	v_pk_fma_f32 v[94:95], v[4:5], v[26:27], v[94:95] op_sel:[0,1,0] op_sel_hi:[1,1,1]
	v_pk_fma_f32 v[78:79], v[6:7], v[32:33], v[78:79] op_sel_hi:[1,0,1]
	v_pk_fma_f32 v[94:95], v[6:7], v[28:29], v[94:95] op_sel_hi:[1,0,1]
	v_pk_fma_f32 v[78:79], v[8:9], v[32:33], v[78:79] op_sel:[0,1,0] op_sel_hi:[1,1,1]
	v_pk_mul_f32 v[82:83], v[76:77], v[38:39] op_sel_hi:[1,0]
	v_pk_fma_f32 v[94:95], v[8:9], v[28:29], v[94:95] op_sel:[0,1,0] op_sel_hi:[1,1,1]
	v_pk_mul_f32 v[84:85], v[76:77], v[38:39] op_sel:[0,1] op_sel_hi:[1,1]
	v_add_f32_dpp v78, v78, v78 quad_perm:[1,0,3,2] row_mask:0xf bank_mask:0xf bound_ctrl:1
	v_add_f32_dpp v79, v79, v79 quad_perm:[1,0,3,2] row_mask:0xf bank_mask:0xf bound_ctrl:1
	v_pk_mul_f32 v[86:87], v[76:77], v[40:41] op_sel_hi:[1,0]
	v_add_f32_dpp v78, v78, v78 quad_perm:[2,3,0,1] row_mask:0xf bank_mask:0xf bound_ctrl:1
	v_add_f32_dpp v79, v79, v79 quad_perm:[2,3,0,1] row_mask:0xf bank_mask:0xf bound_ctrl:1
	v_pk_mul_f32 v[88:89], v[76:77], v[40:41] op_sel:[0,1] op_sel_hi:[1,1]
	v_add_f32_dpp v78, v78, v78 row_half_mirror row_mask:0xf bank_mask:0xf bound_ctrl:1
	v_add_f32_dpp v79, v79, v79 row_half_mirror row_mask:0xf bank_mask:0xf bound_ctrl:1
	v_pk_fma_f32 v[82:83], v[2:3], v[34:35], v[82:83] op_sel_hi:[1,0,1]
	v_add_f32_dpp v78, v78, v78 row_mirror row_mask:0xf bank_mask:0xf bound_ctrl:1
	v_add_f32_dpp v79, v79, v79 row_mirror row_mask:0xf bank_mask:0xf bound_ctrl:1
	v_pk_fma_f32 v[84:85], v[4:5], v[34:35], v[84:85] op_sel:[0,1,0] op_sel_hi:[1,1,1]
	v_pk_fma_f32 v[86:87], v[6:7], v[36:37], v[86:87] op_sel_hi:[1,0,1]
	v_pk_fma_f32 v[88:89], v[8:9], v[36:37], v[88:89] op_sel:[0,1,0] op_sel_hi:[1,1,1]
	v_add_f32_dpp v120, v120, v120 row_ror:4 row_mask:0xf bank_mask:0xf bound_ctrl:1
	v_add_f32_dpp v121, v121, v121 row_ror:4 row_mask:0xf bank_mask:0xf bound_ctrl:1
	s_nop 0
	v_add_f32_dpp v120, v120, v120 row_ror:8 row_mask:0xf bank_mask:0xf bound_ctrl:1
	v_pk_fma_f32 v[2:3], v[78:79], v[42:43], v[82:83] op_sel_hi:[1,0,1]
	v_pk_fma_f32 v[4:5], v[78:79], v[42:43], v[84:85] op_sel:[0,1,0] op_sel_hi:[1,1,1]
	v_pk_fma_f32 v[6:7], v[78:79], v[44:45], v[86:87] op_sel_hi:[1,0,1]
	v_pk_fma_f32 v[8:9], v[78:79], v[44:45], v[88:89] op_sel:[0,1,0] op_sel_hi:[1,1,1]
	v_add_f32_dpp v121, v121, v121 row_ror:8 row_mask:0xf bank_mask:0xf bound_ctrl:1
	global_store_dwordx2 v102, v[120:121], s[10:11]
	v_add_u32_e32 v102, s13, v102
	v_pk_mul_f32 v[96:97], v[2:3], v[46:47] op_sel_hi:[1,0]
	v_pk_fma_f32 v[96:97], v[4:5], v[46:47], v[96:97] op_sel:[0,1,0] op_sel_hi:[1,1,1]
	v_pk_fma_f32 v[96:97], v[6:7], v[48:49], v[96:97] op_sel_hi:[1,0,1]
	v_pk_fma_f32 v[96:97], v[8:9], v[48:49], v[96:97] op_sel:[0,1,0] op_sel_hi:[1,1,1]
	v_cndmask_b32_e64 v104, v90, v92, s[50:51]
	v_cndmask_b32_e64 v106, v92, v90, s[50:51]
	v_cndmask_b32_e64 v108, v94, v96, s[50:51]
	v_cndmask_b32_e64 v110, v96, v94, s[50:51]
	v_cndmask_b32_e64 v105, v91, v93, s[50:51]
	v_cndmask_b32_e64 v107, v93, v91, s[50:51]
	v_cndmask_b32_e64 v109, v95, v97, s[50:51]
	v_cndmask_b32_e64 v111, v97, v95, s[50:51]
	v_add_f32_dpp v112, v106, v104 quad_perm:[1,0,3,2] row_mask:0xf bank_mask:0xf bound_ctrl:1
	v_add_f32_dpp v114, v110, v108 quad_perm:[1,0,3,2] row_mask:0xf bank_mask:0xf bound_ctrl:1
	v_add_f32_dpp v113, v107, v105 quad_perm:[1,0,3,2] row_mask:0xf bank_mask:0xf bound_ctrl:1
	v_add_f32_dpp v115, v111, v109 quad_perm:[1,0,3,2] row_mask:0xf bank_mask:0xf bound_ctrl:1
	v_cndmask_b32_e64 v116, v112, v114, s[52:53]
	v_cndmask_b32_e64 v118, v114, v112, s[52:53]
	v_cndmask_b32_e64 v117, v113, v115, s[52:53]
	v_cndmask_b32_e64 v119, v115, v113, s[52:53]
	v_add_f32_dpp v120, v118, v116 quad_perm:[2,3,0,1] row_mask:0xf bank_mask:0xf bound_ctrl:1
	s_nop 0
	v_add_f32_dpp v121, v119, v117 quad_perm:[2,3,0,1] row_mask:0xf bank_mask:0xf bound_ctrl:1
	v_add_f32_dpp v120, v120, v120 row_ror:4 row_mask:0xf bank_mask:0xf bound_ctrl:1
	s_nop 0
	v_add_f32_dpp v121, v121, v121 row_ror:4 row_mask:0xf bank_mask:0xf bound_ctrl:1
	v_add_f32_dpp v120, v120, v120 row_ror:8 row_mask:0xf bank_mask:0xf bound_ctrl:1
	s_nop 0
	v_add_f32_dpp v121, v121, v121 row_ror:8 row_mask:0xf bank_mask:0xf bound_ctrl:1
	global_store_dwordx2 v102, v[120:121], s[10:11]
	v_add_u32_e32 v102, s13, v102
	s_xor_b32 s14, s14, 0xc000
	s_add_i32 s12, s12, 1
	s_cmp_lt_u32 s12, 0x80
	s_cbranch_scc1 .Lr3_chunk
; __device__ __forceinline__ void phase_scan(CParams& P, LAS unsigned char* lds) {
;     ...
;             __builtin_amdgcn_s_setprio(0);
;             __syncthreads();
;         }
;     }
;     __syncthreads();
	s_branch .LBB0_626
